# v110 + S5 C_re/C_im loads (first used in the pass-2 preamble) issued at the start of the carry phase instead of before pass 1; counted waits re-derived
# speedup vs baseline: 1.0066x; 1.0057x over previous
; #define LAS __attribute__((address_space(3)))
; __device__ __forceinline__ bf16x8 pack8(f32x4 lo, f32x4 hi) { v4u w; w.x = pk2(lo[0], lo[1]); w.y = pk2(lo[2], lo[3]); w.z = pk2(hi[0], hi[1]); w.w = pk2(hi[2], hi[3]); return __builtin_bit_cast(bf16x8, w); }
; __device__ __forceinline__ void gmlp_compute(GmlpRegs& R, const Args& a, const Ctx& C, int c, int hd) {
;     ...
;     const float lg = R.lg, lb = R.lb;
;     bf16x8 af[4];
; #pragma unroll
;     for (int ks = 0; ks < 4; ++ks) { f32x4 lo, hi;
; #pragma unroll
;         for (int e = 0; e < 8; ++e) { const int sl = 32 * ks + 8 * q + e;
;             const float v = __uint_as_float((unsigned)*(const LAS unsigned short*)(VL + sl * 260 + (16 * w + fr) * 2) << 16);
;             const float x = (v - ST[2 * sl]) * ST[2 * sl + 1] * lg + lb; if (e < 4) lo[e] = x; else hi[e - 4] = x; }
;         af[ks] = pack8(lo, hi); }
.LBB0_973:
	s_or_b64 exec, exec, s[4:5]
	s_waitcnt lgkmcnt(0)
	s_barrier
	v_add_u32_e32 v18, v165, v184
	ds_read_b128 v[2:5], v183
	ds_read_u16 v6, v18 offset:34816
	ds_read_u16 v7, v18 offset:35076
	ds_read_u16 v14, v18 offset:35596
	ds_read_u16 v15, v18 offset:36116
	ds_read_u16 v19, v18 offset:36636
	ds_read_u16 v20, v18 offset:43396
	ds_read_u16 v21, v18 offset:43916
	ds_read_u16 v22, v18 offset:44436
	s_waitcnt lgkmcnt(6)
	v_lshlrev_b32_e32 v11, 16, v7
	v_lshlrev_b32_e32 v10, 16, v6
	ds_read_b128 v[6:9], v168
	v_mov_b32_e32 v12, v2
	v_mov_b32_e32 v13, v4
	v_pk_add_f32 v[10:11], v[10:11], v[12:13] neg_lo:[0,1] neg_hi:[0,1]
	v_mov_b32_e32 v4, v3
	v_pk_mul_f32 v[2:3], v[4:5], v[10:11]
	s_waitcnt lgkmcnt(0)
	v_mov_b32_e32 v5, v8
	v_pk_fma_f32 v[10:11], v[98:99], v[2:3], v[100:101]
	v_add_u32_e32 v2, v165, v167
	v_lshlrev_b32_e32 v3, 16, v14
	ds_read_u16 v4, v2 offset:34816
	ds_read_u16 v14, v2 offset:35336
	ds_read_u16 v23, v2 offset:35856
	ds_read_u16 v24, v2 offset:42616
	ds_read_u16 v25, v2 offset:43136
	ds_read_u16 v113, v18 offset:61596
	s_waitcnt lgkmcnt(5)
	v_lshlrev_b32_e32 v2, 16, v4
	v_mov_b32_e32 v4, v6
	v_pk_add_f32 v[2:3], v[2:3], v[4:5] neg_lo:[0,1] neg_hi:[0,1]
	v_mov_b32_e32 v8, v7
	v_pk_mul_f32 v[6:7], v[8:9], v[2:3]
	ds_read_b128 v[2:5], v163
	v_pk_fma_f32 v[12:13], v[98:99], v[6:7], v[100:101]
	ds_read_b128 v[6:9], v166
	v_lshlrev_b32_e32 v15, 16, v15
	s_waitcnt lgkmcnt(6)
	v_lshlrev_b32_e32 v14, 16, v14
	s_waitcnt lgkmcnt(1)
	v_mov_b32_e32 v16, v2
	v_mov_b32_e32 v17, v4
	v_pk_add_f32 v[14:15], v[14:15], v[16:17] neg_lo:[0,1] neg_hi:[0,1]
	v_mov_b32_e32 v4, v3
	v_pk_mul_f32 v[2:3], v[4:5], v[14:15]
	s_waitcnt lgkmcnt(0)
	v_mov_b32_e32 v14, v6
	v_pk_fma_f32 v[4:5], v[98:99], v[2:3], v[100:101]
	v_lshlrev_b32_e32 v3, 16, v19
	v_lshlrev_b32_e32 v2, 16, v23
	v_mov_b32_e32 v15, v8
	v_pk_add_f32 v[2:3], v[2:3], v[14:15] neg_lo:[0,1] neg_hi:[0,1]
	v_mov_b32_e32 v8, v7
	v_pk_mul_f32 v[2:3], v[8:9], v[2:3]
	ds_read_b128 v[6:9], v185
	v_pk_fma_f32 v[14:15], v[98:99], v[2:3], v[100:101]
	v_cvt_pk_bf16_f32 v2, v10, v11
	v_cvt_pk_bf16_f32 v3, v12, v13
	ds_read_b128 v[10:13], v186
	v_cvt_pk_bf16_f32 v4, v4, v5
	v_cvt_pk_bf16_f32 v5, v14, v15
	v_lshlrev_b32_e32 v15, 16, v20
	v_lshlrev_b32_e32 v14, 16, v24
	s_waitcnt lgkmcnt(1)
	v_mov_b32_e32 v16, v6
	v_mov_b32_e32 v17, v8
	v_pk_add_f32 v[14:15], v[14:15], v[16:17] neg_lo:[0,1] neg_hi:[0,1]
	v_mov_b32_e32 v8, v7
	v_pk_mul_f32 v[6:7], v[8:9], v[14:15]
	s_waitcnt lgkmcnt(0)
	v_mov_b32_e32 v8, v10
	v_pk_fma_f32 v[14:15], v[98:99], v[6:7], v[100:101]
	v_lshlrev_b32_e32 v7, 16, v21
	v_lshlrev_b32_e32 v6, 16, v25
	v_mov_b32_e32 v9, v12
	v_pk_add_f32 v[16:17], v[6:7], v[8:9] neg_lo:[0,1] neg_hi:[0,1]
	ds_read_u16 v19, v187 offset:34816
	ds_read_u16 v20, v187 offset:35336
	ds_read_u16 v21, v187 offset:42096
	ds_read_b128 v[6:9], v188
	v_mov_b32_e32 v12, v11
	v_pk_mul_f32 v[10:11], v[12:13], v[16:17]
	v_lshlrev_b32_e32 v13, 16, v22
	s_waitcnt lgkmcnt(3)
	v_lshlrev_b32_e32 v12, 16, v19
	s_waitcnt lgkmcnt(0)
	v_mov_b32_e32 v16, v6
	v_mov_b32_e32 v17, v8
	v_pk_add_f32 v[12:13], v[12:13], v[16:17] neg_lo:[0,1] neg_hi:[0,1]
	v_mov_b32_e32 v8, v7
	v_pk_mul_f32 v[6:7], v[8:9], v[12:13]
	v_pk_fma_f32 v[10:11], v[98:99], v[10:11], v[100:101]
	v_pk_fma_f32 v[12:13], v[98:99], v[6:7], v[100:101]
	ds_read_b128 v[6:9], v189
	ds_read_u16 v16, v18 offset:44956
	ds_read_u16 v22, v18 offset:51716
	ds_read_u16 v23, v18 offset:52236
	ds_read_u16 v24, v18 offset:52756
	ds_read_u16 v26, v18 offset:53276
	ds_read_u16 v27, v18 offset:60036
	ds_read_u16 v28, v18 offset:60556
	ds_read_u16 v36, v18 offset:61076
	s_waitcnt lgkmcnt(7)
	v_lshlrev_b32_e32 v17, 16, v16
	v_lshlrev_b32_e32 v16, 16, v20
	v_mov_b32_e32 v18, v6
	v_mov_b32_e32 v19, v8
	v_pk_add_f32 v[16:17], v[16:17], v[18:19] neg_lo:[0,1] neg_hi:[0,1]
	v_mov_b32_e32 v8, v7
	v_pk_mul_f32 v[6:7], v[8:9], v[16:17]
	ds_read_u16 v25, v187 offset:42616
	ds_read_u16 v29, v187 offset:43136
	v_pk_fma_f32 v[16:17], v[98:99], v[6:7], v[100:101]
	v_cvt_pk_bf16_f32 v7, v10, v11
	v_cvt_pk_bf16_f32 v8, v12, v13
	ds_read_b128 v[10:13], v190
	v_cvt_pk_bf16_f32 v6, v14, v15
	v_cvt_pk_bf16_f32 v9, v16, v17
	ds_read_b128 v[14:17], v191
	s_waitcnt lgkmcnt(10)
	v_lshlrev_b32_e32 v19, 16, v22
	v_lshlrev_b32_e32 v18, 16, v21
	s_waitcnt lgkmcnt(1)
	v_mov_b32_e32 v20, v10
	v_mov_b32_e32 v21, v12
	v_pk_add_f32 v[18:19], v[18:19], v[20:21] neg_lo:[0,1] neg_hi:[0,1]
	v_mov_b32_e32 v12, v11
	v_pk_mul_f32 v[10:11], v[12:13], v[18:19]
	s_waitcnt lgkmcnt(0)
	v_mov_b32_e32 v12, v14
	v_pk_fma_f32 v[18:19], v[98:99], v[10:11], v[100:101]
	v_lshlrev_b32_e32 v11, 16, v23
	v_lshlrev_b32_e32 v10, 16, v25
	v_mov_b32_e32 v13, v16
	v_pk_add_f32 v[10:11], v[10:11], v[12:13] neg_lo:[0,1] neg_hi:[0,1]
	v_mov_b32_e32 v16, v15
	v_pk_mul_f32 v[14:15], v[16:17], v[10:11]
	ds_read_b128 v[10:13], v192
	v_pk_fma_f32 v[20:21], v[98:99], v[14:15], v[100:101]
	ds_read_b128 v[14:17], v194
	v_lshlrev_b32_e32 v23, 16, v24
	v_lshlrev_b32_e32 v22, 16, v29
	s_waitcnt lgkmcnt(1)
	v_mov_b32_e32 v24, v10
	v_mov_b32_e32 v25, v12
	v_pk_add_f32 v[22:23], v[22:23], v[24:25] neg_lo:[0,1] neg_hi:[0,1]
	v_mov_b32_e32 v12, v11
	v_pk_mul_f32 v[10:11], v[12:13], v[22:23]
	s_waitcnt lgkmcnt(0)
	v_mov_b32_e32 v22, v14
	v_pk_fma_f32 v[12:13], v[98:99], v[10:11], v[100:101]
	ds_read_u16 v10, v193 offset:34816
	ds_read_u16 v24, v193 offset:41576
	ds_read_u16 v29, v193 offset:42096
	ds_read_u16 v38, v193 offset:42616
	ds_read_u16 v121, v193 offset:43136
	v_lshlrev_b32_e32 v11, 16, v26
	s_waitcnt lgkmcnt(4)
; #define LAS __attribute__((address_space(3)))
; #define MFMA16(A, B, Cc) __builtin_amdgcn_mfma_f32_16x16x32_bf16((A), (B), (Cc), 0, 0, 0)
; #define PIN(x) asm volatile("" : "+v"(x))
; __device__ __forceinline__ float bf_lo(unsigned w) { return __uint_as_float(w << 16); }
; __device__ __forceinline__ unsigned pk4f8(float a, float b, float c, float d) { int p = __builtin_amdgcn_cvt_pk_fp8_f32(sat8(a), sat8(b), 0, false); p = __builtin_amdgcn_cvt_pk_fp8_f32(sat8(c), sat8(d), p, true); return (unsigned)p; }
; __device__ __forceinline__ float bf_hi(unsigned w) { return __uint_as_float(w & 0xffff0000u); }
; __device__ __forceinline__ bf16x8 pack8(f32x4 lo, f32x4 hi) { v4u w; w.x = pk2(lo[0], lo[1]); w.y = pk2(lo[2], lo[3]); w.z = pk2(hi[0], hi[1]); w.w = pk2(hi[2], hi[3]); return __builtin_bit_cast(bf16x8, w); }
; __device__ __forceinline__ void gmlp_compute(GmlpRegs& R, const Args& a, const Ctx& C, int c, int hd) {
;     ...
;     for (int ks = 0; ks < 4; ++ks) { f32x4 lo, hi;
; #pragma unroll
;         for (int e = 0; e < 8; ++e) { const int sl = 32 * ks + 8 * q + e;
;             const float v = __uint_as_float((unsigned)*(const LAS unsigned short*)(VL + sl * 260 + (16 * w + fr) * 2) << 16);
;             const float x = (v - ST[2 * sl]) * ST[2 * sl + 1] * lg + lb; if (e < 4) lo[e] = x; else hi[e - 4] = x; }
;         af[ks] = pack8(lo, hi); }
;     f32x4 acc[8];
; #pragma unroll
;     for (int nt = 0; nt < 8; ++nt) { acc[nt] = (f32x4){0.f, 0.f, 0.f, 0.f};
; #pragma unroll
;         for (int ks = 0; ks <= nt / 2; ++ks) acc[nt] = MFMA16(af[ks], *(const LAS bf16x8*)(WL + (16 * nt + fr) * 272 + (32 * ks + 8 * q) * 2), acc[nt]); }
; #pragma unroll
;     for (int nt = 0; nt < 8; ++nt) PIN(R.uq[nt]);
; #pragma unroll
;     for (int nt = 0; nt < 8; ++nt) { const size_t row = T0 + 16 * nt + fr; const float bs = R.bsv[nt];
;         const float o0 = bf_lo(R.uq[nt].x) * (acc[nt][0] + bs), o1 = bf_hi(R.uq[nt].x) * (acc[nt][1] + bs);
;         const float o2 = bf_lo(R.uq[nt].y) * (acc[nt][2] + bs), o3 = bf_hi(R.uq[nt].y) * (acc[nt][3] + bs);
;         *(unsigned*)((unsigned char*)Y + row * DM + chs) = pk4f8(o0, o1, o2, o3); }
	v_lshlrev_b32_e32 v10, 16, v10
	v_mov_b32_e32 v23, v16
	v_pk_add_f32 v[10:11], v[10:11], v[22:23] neg_lo:[0,1] neg_hi:[0,1]
	v_mov_b32_e32 v16, v15
	v_pk_mul_f32 v[10:11], v[16:17], v[10:11]
	ds_read_b128 v[14:17], v195
	v_pk_fma_f32 v[22:23], v[98:99], v[10:11], v[100:101]
	v_cvt_pk_bf16_f32 v10, v18, v19
	v_cvt_pk_bf16_f32 v11, v20, v21
	v_cvt_pk_bf16_f32 v12, v12, v13
	v_cvt_pk_bf16_f32 v13, v22, v23
	v_lshlrev_b32_e32 v23, 16, v27
	s_waitcnt lgkmcnt(4)
	v_lshlrev_b32_e32 v22, 16, v24
	ds_read_b128 v[18:21], v196
	s_waitcnt lgkmcnt(1)
	v_mov_b32_e32 v24, v14
	v_mov_b32_e32 v25, v16
	v_pk_add_f32 v[26:27], v[22:23], v[24:25] neg_lo:[0,1] neg_hi:[0,1]
	v_mov_b32_e32 v16, v15
	v_add_u32_e32 v126, v199, v200
	v_pk_mul_f32 v[14:15], v[16:17], v[26:27]
	v_lshlrev_b32_e32 v31, 16, v28
	v_lshlrev_b32_e32 v30, 16, v29
	ds_read_b128 v[26:29], v126 offset:8704
	s_waitcnt lgkmcnt(1)
	v_mov_b32_e32 v32, v18
	v_mov_b32_e32 v33, v20
	v_pk_add_f32 v[34:35], v[30:31], v[32:33] neg_lo:[0,1] neg_hi:[0,1]
	ds_read_b128 v[30:33], v126 offset:8768
	v_mov_b32_e32 v20, v19
	s_waitcnt lgkmcnt(1)
	v_mfma_f32_16x16x32_bf16 v[26:29], v[2:5], v[26:29], 0
	v_mul_f32_e64 v34, v20, v34
	v_mul_f32_e64 v35, v21, v35
	ds_read_b128 v[18:21], v126 offset:13056
	v_lshlrev_b32_e32 v46, 16, v38
	ds_read_b128 v[38:41], v126 offset:17408
	ds_read_b128 v[42:45], v126 offset:17472
	s_waitcnt lgkmcnt(3)
	v_mfma_f32_16x16x32_bf16 v[26:29], v[6:9], v[30:33], v[26:29]
	v_fma_f32 v92, v98, v34, v100
	v_fma_f32 v93, v99, v35, v101
	v_lshlrev_b32_e32 v47, 16, v36
	ds_read_b128 v[30:33], v126 offset:13120
	ds_read_b128 v[34:37], v197
	s_waitcnt lgkmcnt(4)
	v_mfma_f32_16x16x32_bf16 v[18:21], v[2:5], v[18:21], 0
	v_fma_f32 v88, v98, v14, v100
	v_fma_f32 v89, v99, v15, v101
	ds_read_b128 v[22:25], v126
	ds_read_b128 v[14:17], v126 offset:4352
	s_waitcnt lgkmcnt(5)
	v_mfma_f32_16x16x32_bf16 v[38:41], v[2:5], v[38:41], 0
	s_lshl_b64 s[4:5], s[70:71], 11
	s_mov_b64 s[8:9], 0x2300000
	v_readlane_b32 s16, v249, 1
	s_waitcnt lgkmcnt(3)
	v_mfma_f32_16x16x32_bf16 v[18:21], v[6:9], v[30:33], v[18:21]
	ds_read_b128 v[30:33], v198
	s_waitcnt lgkmcnt(3)
	v_mov_b32_e32 v48, v34
	v_mov_b32_e32 v49, v36
	v_pk_add_f32 v[90:91], v[46:47], v[48:49] neg_lo:[0,1] neg_hi:[0,1]
	v_mov_b32_e32 v36, v35
	ds_read_b128 v[46:49], v126 offset:17536
	v_mfma_f32_16x16x32_bf16 v[38:41], v[6:9], v[42:45], v[38:41]
	v_mul_f32_e64 v42, v36, v90
	v_mul_f32_e64 v43, v37, v91
	ds_read_b128 v[34:37], v126 offset:21760
	v_pk_fma_f32 v[122:123], v[98:99], v[42:43], v[100:101]
	ds_read_b128 v[42:45], v126 offset:21824
	s_waitcnt lgkmcnt(1)
	v_mfma_f32_16x16x32_bf16 v[34:37], v[2:5], v[34:37], 0
	v_lshlrev_b32_e32 v91, 16, v113
	v_lshlrev_b32_e32 v90, 16, v121
	v_mov_b32_e32 v124, v30
	v_mfma_f32_16x16x32_bf16 v[38:41], v[10:13], v[46:49], v[38:41]
	ds_read_b128 v[46:49], v126 offset:21888
	v_mov_b32_e32 v125, v32
	v_pk_add_f32 v[90:91], v[90:91], v[124:125] neg_lo:[0,1] neg_hi:[0,1]
	s_waitcnt lgkmcnt(1)
	v_mfma_f32_16x16x32_bf16 v[34:37], v[6:9], v[42:45], v[34:37]
	ds_read_b128 v[42:45], v126 offset:26112
	v_mov_b32_e32 v32, v31
	v_readlane_b32 s17, v249, 2
	s_waitcnt lgkmcnt(1)
	v_mfma_f32_16x16x32_bf16 v[34:37], v[10:13], v[46:49], v[34:37]
	v_mul_f32_e64 v46, v32, v90
	v_mul_f32_e64 v47, v33, v91
	ds_read_b128 v[30:33], v126 offset:26176
	v_pk_fma_f32 v[98:99], v[98:99], v[46:47], v[100:101]
	s_waitcnt lgkmcnt(1)
	v_mfma_f32_16x16x32_bf16 v[42:45], v[2:5], v[42:45], 0
	v_cvt_pk_bf16_f32 v46, v88, v89
	ds_read_b128 v[88:91], v126 offset:26240
	v_cvt_pk_bf16_f32 v47, v92, v93
	s_waitcnt lgkmcnt(1)
	v_mfma_f32_16x16x32_bf16 v[30:33], v[6:9], v[30:33], v[42:45]
	v_cvt_pk_bf16_f32 v48, v122, v123
	v_cvt_pk_bf16_f32 v49, v98, v99
	v_readlane_b32 s18, v249, 3
	ds_read_b128 v[42:45], v126 offset:26304
	s_waitcnt lgkmcnt(1)
	v_mfma_f32_16x16x32_bf16 v[30:33], v[10:13], v[88:91], v[30:33]
	v_readlane_b32 s19, v249, 4
	v_readlane_b32 s20, v249, 5
	v_readlane_b32 s21, v249, 6
	s_waitcnt lgkmcnt(0)
	v_mfma_f32_16x16x32_bf16 v[30:33], v[46:49], v[42:45], v[30:33]
	ds_read_b128 v[42:45], v126 offset:30464
	ds_read_b128 v[88:91], v126 offset:30528
	v_readlane_b32 s22, v249, 7
	v_readlane_b32 s23, v249, 8
	v_mfma_f32_16x16x32_bf16 v[22:25], v[2:5], v[22:25], 0
	v_readlane_b32 s24, v249, 9
	v_readlane_b32 s25, v249, 10
	v_readlane_b32 s26, v249, 11
	v_mfma_f32_16x16x32_bf16 v[14:17], v[2:5], v[14:17], 0
	v_readlane_b32 s27, v249, 12
	v_readlane_b32 s28, v249, 13
	v_readlane_b32 s29, v249, 14
	s_waitcnt lgkmcnt(1)
	v_mfma_f32_16x16x32_bf16 v[2:5], v[2:5], v[42:45], 0
	v_readlane_b32 s30, v249, 15
	v_readlane_b32 s31, v249, 16
	s_mov_b64 s[14:15], s[22:23]
	s_waitcnt lgkmcnt(0)
	v_mfma_f32_16x16x32_bf16 v[2:5], v[6:9], v[88:91], v[2:5]
	ds_read_b128 v[6:9], v126 offset:30592
	ds_read_b128 v[42:45], v126 offset:30656
	s_waitcnt vmcnt(17)
	s_waitcnt vmcnt(16)
	s_waitcnt lgkmcnt(1)
	v_mfma_f32_16x16x32_bf16 v[2:5], v[10:13], v[6:9], v[2:5]
	v_lshlrev_b32_e32 v6, 16, v110
	v_add_f32_e32 v7, v161, v22
	v_mul_f32_e32 v6, v7, v6
	v_and_b32_e32 v7, 0xffff0000, v110
	v_add_f32_e32 v8, v161, v23
	v_mul_f32_e32 v7, v8, v7
	v_med3_f32 v6, v6, s1, v128
	v_med3_f32 v7, v7, s1, v128
	v_mov_b32_e32 v11, 0
	v_lshlrev_b32_e32 v8, 16, v111
	v_add_f32_e32 v9, v161, v24
	v_cvt_pk_fp8_f32 v11, v6, v7
	v_mul_f32_e32 v8, v9, v8
	v_and_b32_e32 v9, 0xffff0000, v111
	v_add_f32_e32 v10, v161, v25
	v_mul_f32_e32 v6, v10, v9
	v_med3_f32 v7, v8, s1, v128
	v_med3_f32 v6, v6, s1, v128
	v_cvt_pk_fp8_f32 v11, v7, v6 op_sel:[0,0,1]
	v_lshlrev_b32_e32 v8, 16, v118
	v_add_f32_e32 v9, v160, v14
	v_mul_f32_e32 v8, v9, v8
	v_and_b32_e32 v9, 0xffff0000, v118
	v_add_f32_e32 v10, v160, v15
	v_lshlrev_b64 v[6:7], 11, v[116:117]
	v_and_b32_e32 v231, 0x7f, v116
	v_and_b32_e32 v232, 0xffffff80, v116
	s_movk_i32 s88, 0x90
	v_mad_u32_u24 v233, v231, s88, v230
	v_add_u32_e32 v233, 0x12000, v233
	v_mul_f32_e32 v9, v10, v9
	v_lshl_add_u64 v[6:7], v[142:143], 0, v[6:7]
	v_med3_f32 v8, v8, s1, v128
	v_med3_f32 v9, v9, s1, v128
	v_mov_b32_e32 v13, 0
	s_waitcnt vmcnt(15)
; __device__ __forceinline__ float bf_lo(unsigned w) { return __uint_as_float(w << 16); }
; __device__ __forceinline__ unsigned pk4f8(float a, float b, float c, float d) { int p = __builtin_amdgcn_cvt_pk_fp8_f32(sat8(a), sat8(b), 0, false); p = __builtin_amdgcn_cvt_pk_fp8_f32(sat8(c), sat8(d), p, true); return (unsigned)p; }
; __device__ __forceinline__ float bf_hi(unsigned w) { return __uint_as_float(w & 0xffff0000u); }
; __device__ __forceinline__ void gmlp_compute(GmlpRegs& R, const Args& a, const Ctx& C, int c, int hd) {
;     ...
;     for (int nt = 0; nt < 8; ++nt) { const size_t row = T0 + 16 * nt + fr; const float bs = R.bsv[nt];
;         const float o0 = bf_lo(R.uq[nt].x) * (acc[nt][0] + bs), o1 = bf_hi(R.uq[nt].x) * (acc[nt][1] + bs);
;         const float o2 = bf_lo(R.uq[nt].y) * (acc[nt][2] + bs), o3 = bf_hi(R.uq[nt].y) * (acc[nt][3] + bs);
;         *(unsigned*)((unsigned char*)Y + row * DM + chs) = pk4f8(o0, o1, o2, o3); }
	s_waitcnt vmcnt(14)
	s_waitcnt vmcnt(13)
	s_waitcnt vmcnt(12)
	s_waitcnt vmcnt(11)
	s_waitcnt vmcnt(10)
	ds_write_b32 v233, v11
	v_lshlrev_b32_e32 v10, 16, v119
	v_add_f32_e32 v11, v160, v16
	v_cvt_pk_fp8_f32 v13, v8, v9
	v_mul_f32_e32 v10, v11, v10
	v_and_b32_e32 v11, 0xffff0000, v119
	v_add_f32_e32 v12, v160, v17
	v_mul_f32_e32 v8, v12, v11
	v_med3_f32 v9, v10, s1, v128
	v_med3_f32 v8, v8, s1, v128
	v_cvt_pk_fp8_f32 v13, v9, v8 op_sel:[0,0,1]
	v_add_co_u32_e32 v8, vcc, s2, v6
	v_add_f32_e32 v10, v159, v27
	s_nop 0
	v_addc_co_u32_e32 v9, vcc, 0, v7, vcc
	ds_write_b32 v233, v13 offset:2304
	v_lshlrev_b32_e32 v8, 16, v114
	v_add_f32_e32 v9, v159, v26
	v_mul_f32_e32 v8, v9, v8
	v_and_b32_e32 v9, 0xffff0000, v114
	v_mul_f32_e32 v9, v10, v9
	v_med3_f32 v8, v8, s1, v128
	v_med3_f32 v9, v9, s1, v128
	v_mov_b32_e32 v13, 0
	v_lshlrev_b32_e32 v10, 16, v115
	v_add_f32_e32 v11, v159, v28
	v_cvt_pk_fp8_f32 v13, v8, v9
	v_mul_f32_e32 v10, v11, v10
	v_and_b32_e32 v11, 0xffff0000, v115
	v_add_f32_e32 v12, v159, v29
	v_mul_f32_e32 v8, v12, v11
	v_med3_f32 v9, v10, s1, v128
	v_med3_f32 v8, v8, s1, v128
	v_cvt_pk_fp8_f32 v13, v9, v8 op_sel:[0,0,1]
	v_add_co_u32_e32 v8, vcc, s33, v6
	v_add_f32_e32 v10, v156, v19
	s_nop 0
	v_addc_co_u32_e32 v9, vcc, 0, v7, vcc
	ds_write_b32 v233, v13 offset:4608
	v_lshlrev_b32_e32 v8, 16, v108
	v_add_f32_e32 v9, v156, v18
	v_mul_f32_e32 v8, v9, v8
	v_and_b32_e32 v9, 0xffff0000, v108
	v_mul_f32_e32 v9, v10, v9
	v_med3_f32 v8, v8, s1, v128
	v_med3_f32 v9, v9, s1, v128
	v_mov_b32_e32 v13, 0
	v_lshlrev_b32_e32 v10, 16, v109
	v_add_f32_e32 v11, v156, v20
	v_cvt_pk_fp8_f32 v13, v8, v9
	v_mul_f32_e32 v10, v11, v10
	v_and_b32_e32 v11, 0xffff0000, v109
	v_add_f32_e32 v12, v156, v21
	v_mul_f32_e32 v8, v12, v11
	v_med3_f32 v9, v10, s1, v128
	v_med3_f32 v8, v8, s1, v128
	v_cvt_pk_fp8_f32 v13, v9, v8 op_sel:[0,0,1]
	v_add_co_u32_e32 v8, vcc, s74, v6
	v_add_f32_e32 v10, v154, v39
	s_nop 0
	v_addc_co_u32_e32 v9, vcc, 0, v7, vcc
	ds_write_b32 v233, v13 offset:6912
	v_lshlrev_b32_e32 v8, 16, v106
	v_add_f32_e32 v9, v154, v38
	v_mul_f32_e32 v8, v9, v8
	v_and_b32_e32 v9, 0xffff0000, v106
	v_mul_f32_e32 v9, v10, v9
	v_med3_f32 v8, v8, s1, v128
	v_med3_f32 v9, v9, s1, v128
	v_mov_b32_e32 v13, 0
	v_lshlrev_b32_e32 v10, 16, v107
	v_add_f32_e32 v11, v154, v40
	v_cvt_pk_fp8_f32 v13, v8, v9
	v_mul_f32_e32 v10, v11, v10
	v_and_b32_e32 v11, 0xffff0000, v107
	v_add_f32_e32 v12, v154, v41
	v_mul_f32_e32 v8, v12, v11
	v_med3_f32 v9, v10, s1, v128
	v_med3_f32 v8, v8, s1, v128
	v_cvt_pk_fp8_f32 v13, v9, v8 op_sel:[0,0,1]
	v_add_co_u32_e32 v8, vcc, s75, v6
	v_add_f32_e32 v10, v152, v35
	s_nop 0
	v_addc_co_u32_e32 v9, vcc, 0, v7, vcc
	ds_write_b32 v233, v13 offset:9216
	v_lshlrev_b32_e32 v8, 16, v104
	v_add_f32_e32 v9, v152, v34
	v_mul_f32_e32 v8, v9, v8
	v_and_b32_e32 v9, 0xffff0000, v104
	v_mul_f32_e32 v9, v10, v9
	v_med3_f32 v8, v8, s1, v128
	v_med3_f32 v9, v9, s1, v128
	v_mov_b32_e32 v13, 0
	v_lshlrev_b32_e32 v10, 16, v105
	v_add_f32_e32 v11, v152, v36
	v_cvt_pk_fp8_f32 v13, v8, v9
	v_mul_f32_e32 v10, v11, v10
	v_and_b32_e32 v11, 0xffff0000, v105
	v_add_f32_e32 v12, v152, v37
	v_mul_f32_e32 v8, v12, v11
	v_med3_f32 v9, v10, s1, v128
	v_med3_f32 v8, v8, s1, v128
	v_cvt_pk_fp8_f32 v13, v9, v8 op_sel:[0,0,1]
	v_add_co_u32_e32 v8, vcc, s76, v6
	v_add_f32_e32 v10, v151, v31
	s_nop 0
	v_addc_co_u32_e32 v9, vcc, 0, v7, vcc
	ds_write_b32 v233, v13 offset:11520
	v_lshlrev_b32_e32 v8, 16, v102
	v_add_f32_e32 v9, v151, v30
	v_mul_f32_e32 v8, v9, v8
	v_and_b32_e32 v9, 0xffff0000, v102
	v_mul_f32_e32 v9, v10, v9
	v_med3_f32 v8, v8, s1, v128
	v_med3_f32 v9, v9, s1, v128
	v_mov_b32_e32 v13, 0
	v_lshlrev_b32_e32 v10, 16, v103
	v_add_f32_e32 v11, v151, v32
	v_cvt_pk_fp8_f32 v13, v8, v9
	v_mul_f32_e32 v10, v11, v10
	v_and_b32_e32 v11, 0xffff0000, v103
	v_add_f32_e32 v12, v151, v33
	v_mul_f32_e32 v8, v12, v11
	v_med3_f32 v9, v10, s1, v128
	v_med3_f32 v8, v8, s1, v128
	s_waitcnt lgkmcnt(0)
	v_mfma_f32_16x16x32_bf16 v[2:5], v[46:49], v[42:45], v[2:5]
	v_cvt_pk_fp8_f32 v13, v9, v8 op_sel:[0,0,1]
	v_add_co_u32_e32 v8, vcc, s77, v6
	v_mov_b32_e32 v111, 0
	s_nop 0
	v_addc_co_u32_e32 v9, vcc, 0, v7, vcc
	ds_write_b32 v233, v13 offset:13824
	v_lshlrev_b32_e32 v8, 16, v96
	s_nop 0
	v_add_f32_e32 v2, v150, v2
	v_mul_f32_e32 v2, v2, v8
	v_and_b32_e32 v8, 0xffff0000, v96
	v_add_f32_e32 v3, v150, v3
	v_mul_f32_e32 v3, v3, v8
	v_lshlrev_b32_e32 v8, 16, v97
	v_add_f32_e32 v4, v150, v4
	v_mul_f32_e32 v4, v4, v8
	v_and_b32_e32 v8, 0xffff0000, v97
	v_add_f32_e32 v5, v150, v5
	v_med3_f32 v2, v2, s1, v128
	v_med3_f32 v3, v3, s1, v128
	v_mov_b32_e32 v9, 0
	v_cvt_pk_fp8_f32 v9, v2, v3
	v_mul_f32_e32 v2, v5, v8
	v_med3_f32 v3, v4, s1, v128
	v_med3_f32 v2, v2, s1, v128
	s_mul_i32 s1, s0, 0x2100
	s_add_u32 s4, s1, s4
	s_addc_u32 s5, 0, s5
	s_lshl_b64 s[4:5], s[4:5], 5
	s_lshl_b32 s1, s0, 9
	s_lshl_b32 s2, s0, 12
	s_add_u32 s6, s94, s1
	v_cvt_pk_fp8_f32 v9, v3, v2 op_sel:[0,0,1]
	v_add_co_u32_e32 v2, vcc, s78, v6
	v_lshlrev_b32_e32 v110, 2, v153
	s_addc_u32 s7, s95, 0
	v_addc_co_u32_e32 v3, vcc, 0, v7, vcc
	v_lshl_add_u64 v[18:19], s[6:7], 0, v[110:111]
	s_mov_b32 s1, 0x2300000
	v_lshl_add_u64 v[20:21], v[18:19], 0, s[8:9]
	v_add_co_u32_e32 v18, vcc, s1, v18
	ds_write_b32 v233, v9 offset:16128
	s_waitcnt lgkmcnt(0)
	s_barrier
; #define LAS __attribute__((address_space(3)))
; #define PIN(x) asm volatile("" : "+v"(x))
; __device__ __forceinline__ unsigned pk2(float lo, float hi) { return pg8::cvt_pk_bf16(lo, hi); }
; __device__ __forceinline__ bf16x8 pack8(f32x4 lo, f32x4 hi) { v4u w; w.x = pk2(lo[0], lo[1]); w.y = pk2(lo[2], lo[3]); w.z = pk2(hi[0], hi[1]); w.w = pk2(hi[2], hi[3]); return __builtin_bit_cast(bf16x8, w); }
; __device__ __forceinline__ void s5_load_consts(S5C& K, const Args& a, int g, int lane) {
;     const int fr = lane & 15, q = lane >> 4;
;     const float* ABAR = (const float*)(a.ws + WS_S5C + S5C_ABAR) + (size_t)g * 128;
;     const bf16* BBAR = (const bf16*)(a.ws + WS_S5C + S5C_BBAR) + (size_t)g * 2048;
; #pragma unroll
;     for (int j = 0; j < 4; ++j) { const f32x4 x0 = *(const f32x4*)(ABAR + 2 * (16 * j + 4 * q)), x1 = *(const f32x4*)(ABAR + 2 * (16 * j + 4 * q) + 4);
;         K.ar[j] = (f32x4){x0[0], x0[2], x1[0], x1[2]}; K.ai[j] = (f32x4){x0[1], x0[3], x1[1], x1[3]}; }
; #pragma unroll
;     for (int mt = 0; mt < 8; ++mt) K.Bf[mt] = *(const v2u*)(BBAR + (mt * 16 + fr) * 16 + 4 * q);
;     const float* cre = a.in[I_CRE] + ((size_t)g * 16 + fr) * 64; const float* cim = a.in[I_CIM] + ((size_t)g * 16 + fr) * 64;
; #pragma unroll
;     for (int j = 0; j < 4; ++j) { const f32x4 r4 = *(const f32x4*)(cre + 16 * j + 4 * q), i4 = *(const f32x4*)(cim + 16 * j + 4 * q); K.Cf[j] = pack8(r4, -i4); }
;     const float* wg = a.in[I_WGLU] + (size_t)g * 512;
;     { f32x4 v, gt;
; #pragma unroll
;       for (int e = 0; e < 4; ++e) { v[e] = wg[(4 * q + e) * 32 + fr]; gt[e] = wg[(4 * q + e) * 32 + 16 + fr]; }
;       K.Wv = (v2u){pk2(v[0], v[1]), pk2(v[2], v[3])}; K.Wg = (v2u){pk2(gt[0], gt[1]), pk2(gt[2], gt[3])}; }
;     K.dsk = *(const f32x4*)(a.in[I_DSKIP] + g * 16 + 4 * q);
;     K.bv = *(const f32x4*)(a.in[I_BGLU] + g * 32 + 4 * q); K.bg = *(const f32x4*)(a.in[I_BGLU] + g * 32 + 16 + 4 * q);
; __device__ __forceinline__ void s5_prompt_task(const Args& a, const Ctx& C, int b, int g, v4u (&xv)[8]) {
;     ...
;     __syncthreads();
; #pragma unroll
;     for (int i = 0; i < 8; ++i) PIN(xv[i]);
; #pragma unroll
;     for (int i = 0; i < 8; ++i) { const int idx = C.tid + 512 * i, tok = idx >> 1; *(LAS v4u*)(XS + tok * 32 + (tok >> 4) * 16 + (idx & 1) * 16) = xv[i]; }
;     S5C K; s5_load_consts(K, a, g, lane);
;     __syncthreads();
	v_lshrrev_b32_e32 v234, 3, v0
	v_and_b32_e32 v236, 7, v0
	v_lshlrev_b32_e32 v236, 4, v236
	s_movk_i32 s88, 0x90
	v_mad_u32_u24 v221, v234, s88, v236
	v_add_u32_e32 v221, 0x12000, v221
	ds_read_b128 v[238:241], v221
	ds_read_b128 v[242:245], v221 offset:9216
	v_add_u32_e32 v234, v232, v234
	v_mov_b32_e32 v235, 0
	v_mov_b32_e32 v237, 0
	v_lshlrev_b64 v[246:247], 11, v[234:235]
	v_lshl_add_u64 v[246:247], v[228:229], 0, v[246:247]
	v_lshl_add_u64 v[246:247], v[246:247], 0, v[236:237]
	v_mov_b32_e32 v236, 0x20000
	v_lshl_add_u64 v[212:213], v[246:247], 0, v[236:237]
	s_waitcnt lgkmcnt(0)
	global_store_dwordx4 v[246:247], v[238:241], off
	global_store_dwordx4 v[212:213], v[242:245], off
	s_nop 0
	v_addc_co_u32_e32 v19, vcc, 0, v19, vcc
	s_barrier
	s_waitcnt vmcnt(9)
	s_waitcnt vmcnt(8)
	s_waitcnt vmcnt(7)
	s_waitcnt vmcnt(6)
	s_waitcnt vmcnt(5)
	s_waitcnt vmcnt(4)
	s_waitcnt vmcnt(3)
	s_waitcnt vmcnt(2)
	global_load_dwordx4 v[2:5], v[20:21], off offset:16
	global_load_dwordx4 v[6:9], v[20:21], off offset:144
	global_load_dwordx4 v[10:13], v[20:21], off offset:272
	global_load_dwordx4 v[14:17], v[20:21], off offset:400
	global_load_dwordx4 v[30:33], v[18:19], off
	v_and_b32_e32 v18, 0x1fe0, v94
	v_lshrrev_b32_e32 v19, 1, v0
	v_add_u32_e32 v18, 0, v18
	v_and_b32_e32 v19, 0xf0, v19
	v_and_b32_e32 v24, 16, v94
	v_add3_u32 v18, v18, v19, v24
	ds_write_b128 v18, v[74:77]
	v_and_b32_e32 v18, 0x3fe0, v87
	v_lshrrev_b32_e32 v19, 1, v146
	v_add_u32_e32 v18, 0, v18
	v_and_b32_e32 v19, 0x1f0, v19
	v_add3_u32 v18, v18, v19, v24
	ds_write_b128 v18, v[78:81]
	v_and_b32_e32 v18, 0x7fe0, v148
	v_lshrrev_b32_e32 v19, 1, v147
	v_add_u32_e32 v18, 0, v18
	v_and_b32_e32 v19, 0x3f0, v19
	v_add3_u32 v18, v18, v19, v24
	ds_write_b128 v18, v[70:73]
	v_and_b32_e32 v18, 0x7fe0, v86
	v_lshrrev_b32_e32 v19, 1, v95
	v_add_u32_e32 v18, 0, v18
	v_and_b32_e32 v19, 0x3f0, v19
	v_add3_u32 v18, v18, v19, v24
	ds_write_b128 v18, v[66:69]
	v_and_b32_e32 v18, 0xbfe0, v85
	v_lshrrev_b32_e32 v19, 1, v120
	v_add_u32_e32 v18, 0, v18
	v_and_b32_e32 v19, 0x5f0, v19
	v_add3_u32 v18, v18, v19, v24
	ds_write_b128 v18, v[58:61]
	v_and_b32_e32 v18, 0xffe0, v84
	v_lshrrev_b32_e32 v19, 1, v157
	v_add_u32_e32 v18, 0, v18
	v_and_b32_e32 v19, 0x7f0, v19
	v_add3_u32 v18, v18, v19, v24
	ds_write_b128 v18, v[62:65]
	v_and_b32_e32 v18, 0xffe0, v83
	v_lshrrev_b32_e32 v19, 1, v158
	s_add_u32 s8, s94, s2
	v_add_u32_e32 v18, 0, v18
	v_and_b32_e32 v19, 0x7f0, v19
	s_addc_u32 s9, s95, 0
	v_lshlrev_b32_e32 v110, 1, v112
	v_add3_u32 v25, v18, v19, v24
	v_lshl_add_u64 v[18:19], s[8:9], 0, v[110:111]
	v_lshlrev_b32_e32 v22, 5, v149
	v_mov_b32_e32 v23, v111
	v_lshl_add_u64 v[18:19], v[18:19], 0, v[22:23]
	s_mov_b32 s1, 0x2320000
	v_add_co_u32_e32 v22, vcc, s1, v18
	s_mov_b64 s[8:9], 0x2320000
	s_nop 0
	v_addc_co_u32_e32 v23, vcc, 0, v19, vcc
	global_load_dwordx2 v[114:115], v[22:23], off
	v_lshl_add_u64 v[18:19], v[18:19], 0, s[8:9]
	global_load_dwordx2 v[116:117], v[18:19], off offset:512
	global_load_dwordx4 v[70:73], v[20:21], off offset:128
	v_and_b32_e32 v22, 0xffe0, v82
	v_lshrrev_b32_e32 v23, 1, v155
	global_load_dwordx4 v[74:77], v[20:21], off offset:256
	global_load_dwordx4 v[66:69], v[20:21], off offset:384
	v_add_u32_e32 v22, 0, v22
	v_and_b32_e32 v23, 0x7f0, v23
	v_add3_u32 v22, v22, v23, v24
	ds_write_b128 v25, v[50:53]
	ds_write_b128 v22, v[54:57]
	global_load_dwordx2 v[126:127], v[18:19], off offset:1024
	global_load_dwordx2 v[128:129], v[18:19], off offset:1536
	global_load_dwordx2 v[130:131], v[18:19], off offset:2048
	global_load_dwordx2 v[132:133], v[18:19], off offset:2560
	global_load_dwordx2 v[134:135], v[18:19], off offset:3072
	global_load_dwordx2 v[136:137], v[18:19], off offset:3584
	v_lshl_or_b32 v18, v149, 8, s2
	v_mov_b32_e32 v19, v111
	s_mov_b64 s[16:17], s[24:25]
	v_lshl_add_u64 v[20:21], s[14:15], 0, v[18:19]
	v_lshl_add_u64 v[18:19], s[16:17], 0, v[18:19]
	v_lshlrev_b32_e32 v78, 2, v112
	v_mov_b32_e32 v79, v111
	s_mov_b64 s[20:21], s[28:29]
	v_lshl_add_u64 v[20:21], v[20:21], 0, v[78:79]
	v_lshl_add_u64 v[18:19], v[18:19], 0, v[78:79]
	s_lshl_b32 s1, s0, 11
	s_add_u32 s8, s20, s1
	v_lshlrev_b32_e32 v18, 2, v149
	s_mov_b64 s[18:19], s[26:27]
	s_addc_u32 s9, s21, 0
	v_lshl_or_b32 v18, v145, 9, v18
	s_lshl_b32 s1, s0, 4
	s_lshl_b32 s2, s0, 6
	global_load_dword v191, v18, s[8:9]
	global_load_dword v161, v18, s[8:9] offset:64
	global_load_dword v193, v18, s[8:9] offset:128
	global_load_dword v190, v18, s[8:9] offset:192
	global_load_dword v195, v18, s[8:9] offset:256
	global_load_dword v192, v18, s[8:9] offset:320
	global_load_dword v196, v18, s[8:9] offset:384
	global_load_dword v194, v18, s[8:9] offset:448
	s_add_u32 s8, s18, s2
	s_mov_b64 s[22:23], s[30:31]
	s_addc_u32 s9, s19, 0
	s_lshl_b32 s2, s0, 7
	s_add_u32 s10, s22, s2
	s_movk_i32 s2, 0x210
	v_mul_lo_u32 v102, v144, s2
	v_add3_u32 v163, 0, v102, v153
	s_addc_u32 s11, s23, 0
	global_load_dwordx4 v[18:21], v78, s[8:9]
	global_load_dwordx4 v[22:25], v78, s[10:11]
	global_load_dwordx4 v[26:29], v78, s[10:11] offset:64
	v_readlane_b32 s36, v249, 0
	s_and_b32 s36, s36, 63
	s_lshl_b32 s36, s36, 9
	s_add_u32 s36, s36, 0x2308000
	s_add_u32 s36, s94, s36
	s_addc_u32 s37, s95, 0
	s_add_u32 s38, s36, 0x8000
	s_addc_u32 s39, s37, 0
	v_lshlrev_b32_e32 v238, 3, v162
	s_nop 1
	global_load_dwordx2 v[234:235], v238, s[36:37]
	global_load_dwordx2 v[236:237], v238, s[38:39]
	s_waitcnt lgkmcnt(0)
	s_barrier
; #define LAS __attribute__((address_space(3)))
; #define S5_UPDATE(K, hre, him, xq) do { const v2u xb_ = (xq); \
;     _Pragma("unroll") for (int j = 0; j < 4; ++j) { const f32x4 cre_ = K.ar[j] * hre[j] - K.ai[j] * him[j], cim_ = K.ar[j] * him[j] + K.ai[j] * hre[j]; \
;         hre[j] = MFMA16K16(K.Bf[2 * j], xb_, cre_); him[j] = MFMA16K16(K.Bf[2 * j + 1], xb_, cim_); } } while (0)
; __device__ __forceinline__ void s5_prompt_task(const Args& a, const Ctx& C, int b, int g, v4u (&xv)[8]) {
;     ...
;     const int chunk = 16 * w + n;
;     f32x4 hre[4], him[4];
; #pragma unroll
;     for (int j = 0; j < 4; ++j) { hre[j] = (f32x4){0.f, 0.f, 0.f, 0.f}; him[j] = (f32x4){0.f, 0.f, 0.f, 0.f}; }
;     const LAS unsigned char* xsl = XS + chunk * 528 + q * 8;
;     for (int t = 0; t < 16; ++t) { const v2u xq = *(const LAS v2u*)(xsl + t * 32); S5_UPDATE(K, hre, him, xq); }
	ds_read2_b64 v[104:107], v163 offset1:4
	s_waitcnt vmcnt(24)
	v_mov_b32_e32 v78, v30
	v_mov_b32_e32 v79, v32
	v_mov_b32_e32 v80, v2
	v_mov_b32_e32 v81, v4
	v_pk_mul_f32 v[86:87], v[78:79], 0 op_sel_hi:[1,0]
	v_pk_mul_f32 v[90:91], v[80:81], 0 op_sel_hi:[1,0]
	v_xor_b32_e32 v83, 0x80000000, v33
	v_xor_b32_e32 v82, 0x80000000, v31
	v_xor_b32_e32 v85, 0x80000000, v5
	v_xor_b32_e32 v84, 0x80000000, v3
	v_mov_b32_e32 v118, v3
	v_pk_fma_f32 v[82:83], v[82:83], 0, v[86:87] op_sel_hi:[1,0,1]
	v_pk_fma_f32 v[84:85], v[84:85], 0, v[90:91] op_sel_hi:[1,0,1]
	v_mov_b32_e32 v88, v31
	v_mov_b32_e32 v89, v33
	v_mov_b32_e32 v119, v5
	s_waitcnt vmcnt(23) lgkmcnt(0)
	v_mfma_f32_16x16x16_bf16 v[138:141], v[114:115], v[104:105], v[82:85]
	s_nop 2
	v_fma_f32 v82, v88, 0, v86
	v_fma_f32 v83, v89, 0, v87
	v_pk_fma_f32 v[84:85], v[118:119], 0, v[90:91] op_sel_hi:[1,0,1]
	v_mov_b32_e32 v86, v6
	v_mov_b32_e32 v87, v8
	s_waitcnt vmcnt(22)
	v_mfma_f32_16x16x16_bf16 v[146:149], v[116:117], v[104:105], v[82:85]
	v_mul_f32_e64 v94, v86, 0
	v_mul_f32_e64 v95, v87, 0
	v_xor_b32_e32 v91, 0x80000000, v9
	v_xor_b32_e32 v90, 0x80000000, v7
	s_waitcnt vmcnt(21)
	v_mov_b32_e32 v82, v70
	v_mov_b32_e32 v83, v72
	v_mov_b32_e32 v120, v7
	v_pk_mul_f32 v[84:85], v[82:83], 0 op_sel_hi:[1,0]
	v_pk_fma_f32 v[92:93], v[90:91], 0, v[94:95] op_sel_hi:[1,0,1]
	v_xor_b32_e32 v91, 0x80000000, v73
	v_xor_b32_e32 v90, 0x80000000, v71
	v_mov_b32_e32 v121, v9
	v_pk_fma_f32 v[90:91], v[90:91], 0, v[84:85] op_sel_hi:[1,0,1]
	v_pk_fma_f32 v[98:99], v[120:121], 0, v[94:95] op_sel_hi:[1,0,1]
	v_mov_b32_e32 v94, v71
	v_mov_b32_e32 v95, v73
	s_waitcnt vmcnt(18)
	v_mfma_f32_16x16x16_bf16 v[150:153], v[126:127], v[104:105], v[90:93]
	v_fma_f32 v96, v94, 0, v84
	v_fma_f32 v97, v95, 0, v85
	v_mov_b32_e32 v84, v74
	v_mov_b32_e32 v85, v76
	v_mov_b32_e32 v92, v10
	v_mov_b32_e32 v93, v12
	s_waitcnt vmcnt(17)
	v_mfma_f32_16x16x16_bf16 v[154:157], v[128:129], v[104:105], v[96:99]
	v_mul_f32_e64 v100, v92, 0
	v_mul_f32_e64 v101, v93, 0
	v_pk_mul_f32 v[90:91], v[84:85], 0 op_sel_hi:[1,0]
	v_mov_b32_e32 v122, v11
	v_xor_b32_e32 v97, 0x80000000, v13
	v_xor_b32_e32 v96, 0x80000000, v11
	v_pk_fma_f32 v[98:99], v[96:97], 0, v[100:101] op_sel_hi:[1,0,1]
	v_xor_b32_e32 v97, 0x80000000, v77
	v_xor_b32_e32 v96, 0x80000000, v75
	v_pk_fma_f32 v[96:97], v[96:97], 0, v[90:91] op_sel_hi:[1,0,1]
	v_mov_b32_e32 v123, v13
	v_pk_fma_f32 v[166:167], v[122:123], 0, v[100:101] op_sel_hi:[1,0,1]
	s_waitcnt vmcnt(16)
	v_mfma_f32_16x16x16_bf16 v[168:171], v[130:131], v[104:105], v[96:99]
	v_xor_b32_e32 v143, 0x80000000, v17
	v_xor_b32_e32 v142, 0x80000000, v15
	v_mov_b32_e32 v124, v15
	v_mov_b32_e32 v98, v75
	v_mov_b32_e32 v99, v77
	v_mov_b32_e32 v96, v14
	v_mov_b32_e32 v97, v16
	v_pk_fma_f32 v[164:165], v[98:99], 0, v[90:91] op_sel_hi:[1,0,1]
	v_mov_b32_e32 v90, v66
	v_mov_b32_e32 v91, v68
	v_pk_mul_f32 v[100:101], v[96:97], 0 op_sel_hi:[1,0]
	v_pk_mul_f32 v[108:109], v[90:91], 0 op_sel_hi:[1,0]
	v_pk_fma_f32 v[174:175], v[142:143], 0, v[100:101] op_sel_hi:[1,0,1]
	v_xor_b32_e32 v143, 0x80000000, v69
	v_xor_b32_e32 v142, 0x80000000, v67
	v_mov_b32_e32 v125, v17
	v_pk_fma_f32 v[172:173], v[142:143], 0, v[108:109] op_sel_hi:[1,0,1]
	v_pk_fma_f32 v[176:177], v[124:125], 0, v[100:101] op_sel_hi:[1,0,1]
	v_mov_b32_e32 v100, v67
	v_mov_b32_e32 v101, v69
	s_waitcnt vmcnt(14)
	v_mfma_f32_16x16x16_bf16 v[178:181], v[134:135], v[104:105], v[172:175]
	s_add_i32 s8, 0, 0x10800
	v_add_u32_e32 v3, s8, v102
	v_lshlrev_b32_e32 v7, 5, v145
	v_pk_fma_f32 v[174:175], v[100:101], 0, v[108:109] op_sel_hi:[1,0,1]
	v_mfma_f32_16x16x16_bf16 v[164:167], v[132:133], v[104:105], v[164:167]
	v_mul_f32_e64 v108, v88, v146
	v_mul_f32_e64 v109, v89, v147
	v_add_u32_e32 v3, v3, v7
	v_pk_fma_f32 v[182:183], v[78:79], v[138:139], v[108:109] neg_lo:[0,0,1] neg_hi:[0,0,1]
	s_waitcnt vmcnt(13)
	v_mfma_f32_16x16x16_bf16 v[172:175], v[136:137], v[104:105], v[174:177]
	v_mul_f32_e64 v104, v118, v148
	v_mul_f32_e64 v105, v119, v149
	v_pk_mul_f32 v[108:109], v[78:79], v[146:147]
	v_pk_fma_f32 v[184:185], v[80:81], v[140:141], v[104:105] neg_lo:[0,0,1] neg_hi:[0,0,1]
	v_pk_mul_f32 v[104:105], v[80:81], v[148:149]
	v_pk_fma_f32 v[138:139], v[88:89], v[138:139], v[108:109]
	v_pk_fma_f32 v[140:141], v[118:119], v[140:141], v[104:105]
	v_pk_mul_f32 v[104:105], v[120:121], v[156:157]
	v_pk_mul_f32 v[108:109], v[94:95], v[154:155]
	v_pk_fma_f32 v[148:149], v[86:87], v[152:153], v[104:105] neg_lo:[0,0,1] neg_hi:[0,0,1]
	v_pk_fma_f32 v[146:147], v[82:83], v[150:151], v[108:109] neg_lo:[0,0,1] neg_hi:[0,0,1]
	v_pk_mul_f32 v[104:105], v[86:87], v[156:157]
	v_pk_mul_f32 v[108:109], v[82:83], v[154:155]
	v_pk_fma_f32 v[152:153], v[120:121], v[152:153], v[104:105]
	v_pk_fma_f32 v[150:151], v[94:95], v[150:151], v[108:109]
	v_pk_mul_f32 v[104:105], v[122:123], v[166:167]
	v_pk_mul_f32 v[108:109], v[98:99], v[164:165]
	v_pk_fma_f32 v[156:157], v[92:93], v[170:171], v[104:105] neg_lo:[0,0,1] neg_hi:[0,0,1]
	v_pk_fma_f32 v[154:155], v[84:85], v[168:169], v[108:109] neg_lo:[0,0,1] neg_hi:[0,0,1]
	v_pk_mul_f32 v[104:105], v[92:93], v[166:167]
	v_pk_mul_f32 v[108:109], v[84:85], v[164:165]
	v_pk_fma_f32 v[166:167], v[122:123], v[170:171], v[104:105]
	v_pk_fma_f32 v[164:165], v[98:99], v[168:169], v[108:109]
	v_pk_mul_f32 v[104:105], v[124:125], v[174:175]
	v_pk_mul_f32 v[108:109], v[100:101], v[172:173]
	v_pk_fma_f32 v[170:171], v[96:97], v[180:181], v[104:105] neg_lo:[0,0,1] neg_hi:[0,0,1]
	v_pk_fma_f32 v[168:169], v[90:91], v[178:179], v[108:109] neg_lo:[0,0,1] neg_hi:[0,0,1]
	v_pk_mul_f32 v[104:105], v[96:97], v[174:175]
	v_pk_mul_f32 v[108:109], v[90:91], v[172:173]
	v_mfma_f32_16x16x16_bf16 v[138:141], v[116:117], v[106:107], v[138:141]
	v_fma_f32 v174, v124, v180, v104
	v_fma_f32 v175, v125, v181, v105
	v_pk_fma_f32 v[172:173], v[100:101], v[178:179], v[108:109]
	s_add_u32 s4, s94, s4
	v_mfma_f32_16x16x16_bf16 v[182:185], v[114:115], v[106:107], v[182:185]
	s_addc_u32 s5, s95, s5
	s_nop 1
	v_pk_mul_f32 v[108:109], v[118:119], v[140:141]
	v_pk_mul_f32 v[142:143], v[88:89], v[138:139]
	v_mfma_f32_16x16x16_bf16 v[146:149], v[126:127], v[106:107], v[146:149]
	v_mul_f32_e64 v138, v78, v138
	v_mul_f32_e64 v139, v79, v139
	v_pk_fma_f32 v[178:179], v[80:81], v[184:185], v[108:109] neg_lo:[0,0,1] neg_hi:[0,0,1]
	v_pk_fma_f32 v[176:177], v[78:79], v[182:183], v[142:143] neg_lo:[0,0,1] neg_hi:[0,0,1]
	v_mfma_f32_16x16x16_bf16 v[150:153], v[128:129], v[106:107], v[150:153]
	v_mul_f32_e64 v108, v80, v140
	v_mul_f32_e64 v109, v81, v141
	v_lshlrev_b32_e32 v7, 4, v144
	s_mov_b32 s2, 0x2308000
	v_mfma_f32_16x16x16_bf16 v[154:157], v[130:131], v[106:107], v[154:157]
	v_mov_b32_e32 v160, v111
	v_mfma_f32_16x16x16_bf16 v[164:167], v[132:133], v[106:107], v[164:167]
	v_mfma_f32_16x16x16_bf16 v[168:171], v[134:135], v[106:107], v[168:171]
	v_mfma_f32_16x16x16_bf16 v[104:107], v[136:137], v[106:107], v[172:175]
	s_nop 2
	ds_read2_b64 v[172:175], v163 offset0:8 offset1:12
	s_waitcnt lgkmcnt(0)
; #define LAS __attribute__((address_space(3)))
; #define S5_UPDATE(K, hre, him, xq) do { const v2u xb_ = (xq); \
;     _Pragma("unroll") for (int j = 0; j < 4; ++j) { const f32x4 cre_ = K.ar[j] * hre[j] - K.ai[j] * him[j], cim_ = K.ar[j] * him[j] + K.ai[j] * hre[j]; \
;         hre[j] = MFMA16K16(K.Bf[2 * j], xb_, cre_); him[j] = MFMA16K16(K.Bf[2 * j + 1], xb_, cim_); } } while (0)
; __device__ __forceinline__ void s5_prompt_task(const Args& a, const Ctx& C, int b, int g, v4u (&xv)[8]) {
;     ...
;     const LAS unsigned char* xsl = XS + chunk * 528 + q * 8;
;     for (int t = 0; t < 16; ++t) { const v2u xq = *(const LAS v2u*)(xsl + t * 32); S5_UPDATE(K, hre, him, xq); }
	v_mfma_f32_16x16x16_bf16 v[140:143], v[114:115], v[172:173], v[176:179]
	s_nop 2
	v_fma_f32 v178, v118, v184, v108
	v_fma_f32 v179, v119, v185, v109
	v_pk_fma_f32 v[176:177], v[88:89], v[182:183], v[138:139]
	v_pk_mul_f32 v[108:109], v[120:121], v[152:153]
	v_pk_mul_f32 v[138:139], v[94:95], v[150:151]
	v_pk_fma_f32 v[182:183], v[86:87], v[148:149], v[108:109] neg_lo:[0,0,1] neg_hi:[0,0,1]
	v_pk_fma_f32 v[180:181], v[82:83], v[146:147], v[138:139] neg_lo:[0,0,1] neg_hi:[0,0,1]
	v_pk_mul_f32 v[108:109], v[86:87], v[152:153]
	v_pk_mul_f32 v[138:139], v[82:83], v[150:151]
	v_mfma_f32_16x16x16_bf16 v[176:179], v[116:117], v[172:173], v[176:179]
	v_fma_f32 v148, v120, v148, v108
	v_fma_f32 v149, v121, v149, v109
	v_pk_fma_f32 v[146:147], v[94:95], v[146:147], v[138:139]
	v_pk_mul_f32 v[108:109], v[122:123], v[166:167]
	v_pk_mul_f32 v[138:139], v[98:99], v[164:165]
	v_pk_fma_f32 v[152:153], v[92:93], v[156:157], v[108:109] neg_lo:[0,0,1] neg_hi:[0,0,1]
	v_pk_fma_f32 v[150:151], v[84:85], v[154:155], v[138:139] neg_lo:[0,0,1] neg_hi:[0,0,1]
	v_pk_mul_f32 v[108:109], v[92:93], v[166:167]
	v_pk_mul_f32 v[138:139], v[84:85], v[164:165]
	v_pk_fma_f32 v[156:157], v[122:123], v[156:157], v[108:109]
	v_pk_fma_f32 v[154:155], v[98:99], v[154:155], v[138:139]
	v_pk_mul_f32 v[108:109], v[124:125], v[106:107]
	v_pk_mul_f32 v[138:139], v[100:101], v[104:105]
	v_mfma_f32_16x16x16_bf16 v[146:149], v[128:129], v[172:173], v[146:149]
	v_fma_f32 v166, v96, v170, -v108
	v_fma_f32 v167, v97, v171, -v109
	v_pk_fma_f32 v[164:165], v[90:91], v[168:169], v[138:139] neg_lo:[0,0,1] neg_hi:[0,0,1]
	v_pk_mul_f32 v[138:139], v[96:97], v[106:107]
	v_pk_mul_f32 v[104:105], v[90:91], v[104:105]
	v_mfma_f32_16x16x16_bf16 v[180:183], v[126:127], v[172:173], v[180:183]
	v_mfma_f32_16x16x16_bf16 v[106:109], v[134:135], v[172:173], v[164:167]
	s_nop 2
	v_fma_f32 v166, v124, v170, v138
	v_fma_f32 v167, v125, v171, v139
	v_pk_fma_f32 v[164:165], v[100:101], v[168:169], v[104:105]
	v_pk_mul_f32 v[104:105], v[118:119], v[178:179]
	v_pk_mul_f32 v[138:139], v[88:89], v[176:177]
	v_mfma_f32_16x16x16_bf16 v[154:157], v[132:133], v[172:173], v[154:157]
	v_fma_f32 v170, v80, v142, -v104
	v_fma_f32 v171, v81, v143, -v105
	v_pk_fma_f32 v[168:169], v[78:79], v[140:141], v[138:139] neg_lo:[0,0,1] neg_hi:[0,0,1]
	v_pk_mul_f32 v[104:105], v[80:81], v[178:179]
	v_pk_mul_f32 v[138:139], v[78:79], v[176:177]
	v_mfma_f32_16x16x16_bf16 v[150:153], v[130:131], v[172:173], v[150:153]
	v_fma_f32 v142, v118, v142, v104
	v_fma_f32 v143, v119, v143, v105
	v_pk_fma_f32 v[140:141], v[88:89], v[140:141], v[138:139]
	v_pk_mul_f32 v[104:105], v[120:121], v[148:149]
	v_mfma_f32_16x16x16_bf16 v[164:167], v[136:137], v[172:173], v[164:167]
	v_fma_f32 v178, v86, v182, -v104
	v_fma_f32 v179, v87, v183, -v105
	v_pk_mul_f32 v[104:105], v[86:87], v[148:149]
	v_mfma_f32_16x16x16_bf16 v[138:141], v[116:117], v[174:175], v[140:143]
	v_fma_f32 v148, v120, v182, v104
	v_fma_f32 v149, v121, v183, v105
	v_pk_mul_f32 v[104:105], v[122:123], v[156:157]
	v_pk_mul_f32 v[142:143], v[94:95], v[146:147]
	v_pk_fma_f32 v[182:183], v[92:93], v[152:153], v[104:105] neg_lo:[0,0,1] neg_hi:[0,0,1]
	v_pk_fma_f32 v[176:177], v[82:83], v[180:181], v[142:143] neg_lo:[0,0,1] neg_hi:[0,0,1]
	v_pk_mul_f32 v[142:143], v[82:83], v[146:147]
	v_pk_mul_f32 v[104:105], v[92:93], v[156:157]
	v_pk_fma_f32 v[146:147], v[94:95], v[180:181], v[142:143]
	v_pk_mul_f32 v[142:143], v[98:99], v[154:155]
	v_mfma_f32_16x16x16_bf16 v[168:171], v[114:115], v[174:175], v[168:171]
	v_fma_f32 v180, v84, v150, -v142
	v_fma_f32 v181, v85, v151, -v143
	v_pk_mul_f32 v[142:143], v[84:85], v[154:155]
	v_pk_fma_f32 v[152:153], v[122:123], v[152:153], v[104:105]
	v_pk_fma_f32 v[150:151], v[98:99], v[150:151], v[142:143]
	v_pk_mul_f32 v[104:105], v[124:125], v[166:167]
	v_pk_mul_f32 v[142:143], v[100:101], v[164:165]
	v_mfma_f32_16x16x16_bf16 v[146:149], v[128:129], v[174:175], v[146:149]
	v_mfma_f32_16x16x16_bf16 v[156:159], v[130:131], v[174:175], v[180:183]
	s_nop 2
	v_fma_f32 v182, v96, v108, -v104
	v_fma_f32 v183, v97, v109, -v105
	v_pk_fma_f32 v[180:181], v[90:91], v[106:107], v[142:143] neg_lo:[0,0,1] neg_hi:[0,0,1]
	v_pk_mul_f32 v[104:105], v[96:97], v[166:167]
	v_pk_mul_f32 v[142:143], v[90:91], v[164:165]
	ds_read2_b64 v[164:167], v163 offset0:16 offset1:20
	v_mfma_f32_16x16x16_bf16 v[176:179], v[126:127], v[174:175], v[176:179]
	v_fma_f32 v108, v124, v108, v104
	v_fma_f32 v109, v125, v109, v105
	v_pk_fma_f32 v[106:107], v[100:101], v[106:107], v[142:143]
	v_pk_mul_f32 v[142:143], v[88:89], v[138:139]
	v_mfma_f32_16x16x16_bf16 v[150:153], v[132:133], v[174:175], v[150:153]
	v_mul_f32_e64 v138, v78, v138
	v_mul_f32_e64 v139, v79, v139
	v_pk_fma_f32 v[172:173], v[78:79], v[168:169], v[142:143] neg_lo:[0,0,1] neg_hi:[0,0,1]
	v_pk_fma_f32 v[168:169], v[88:89], v[168:169], v[138:139]
	v_mfma_f32_16x16x16_bf16 v[104:107], v[136:137], v[174:175], v[106:109]
	v_mul_f32_e64 v138, v94, v146
	v_mul_f32_e64 v139, v95, v147
	s_nop 0
	v_pk_mul_f32 v[108:109], v[118:119], v[140:141]
	v_mfma_f32_16x16x16_bf16 v[180:183], v[134:135], v[174:175], v[180:183]
	v_fma_f32 v174, v80, v170, -v108
	v_fma_f32 v175, v81, v171, -v109
	v_pk_mul_f32 v[108:109], v[80:81], v[140:141]
	s_nop 0
	v_pk_fma_f32 v[170:171], v[118:119], v[170:171], v[108:109]
	v_pk_mul_f32 v[108:109], v[120:121], v[148:149]
	s_waitcnt lgkmcnt(0)
; #define LAS __attribute__((address_space(3)))
; #define S5_UPDATE(K, hre, him, xq) do { const v2u xb_ = (xq); \
;     _Pragma("unroll") for (int j = 0; j < 4; ++j) { const f32x4 cre_ = K.ar[j] * hre[j] - K.ai[j] * him[j], cim_ = K.ar[j] * him[j] + K.ai[j] * hre[j]; \
;         hre[j] = MFMA16K16(K.Bf[2 * j], xb_, cre_); him[j] = MFMA16K16(K.Bf[2 * j + 1], xb_, cim_); } } while (0)
; __device__ __forceinline__ void s5_prompt_task(const Args& a, const Ctx& C, int b, int g, v4u (&xv)[8]) {
;     ...
;     const LAS unsigned char* xsl = XS + chunk * 528 + q * 8;
;     for (int t = 0; t < 16; ++t) { const v2u xq = *(const LAS v2u*)(xsl + t * 32); S5_UPDATE(K, hre, him, xq); }
	v_mfma_f32_16x16x16_bf16 v[140:143], v[114:115], v[164:165], v[172:175]
	s_nop 2
	v_fma_f32 v174, v86, v178, -v108
	v_fma_f32 v175, v87, v179, -v109
	v_pk_fma_f32 v[172:173], v[82:83], v[176:177], v[138:139] neg_lo:[0,0,1] neg_hi:[0,0,1]
	v_pk_mul_f32 v[108:109], v[86:87], v[148:149]
	v_pk_mul_f32 v[138:139], v[82:83], v[146:147]
	v_mfma_f32_16x16x16_bf16 v[168:171], v[116:117], v[164:165], v[168:171]
	v_fma_f32 v148, v120, v178, v108
	v_fma_f32 v149, v121, v179, v109
	v_pk_fma_f32 v[146:147], v[94:95], v[176:177], v[138:139]
	v_pk_mul_f32 v[108:109], v[122:123], v[152:153]
	v_pk_mul_f32 v[138:139], v[98:99], v[150:151]
	v_pk_fma_f32 v[178:179], v[92:93], v[158:159], v[108:109] neg_lo:[0,0,1] neg_hi:[0,0,1]
	v_pk_fma_f32 v[176:177], v[84:85], v[156:157], v[138:139] neg_lo:[0,0,1] neg_hi:[0,0,1]
	v_pk_mul_f32 v[108:109], v[92:93], v[152:153]
	v_pk_mul_f32 v[138:139], v[84:85], v[150:151]
	v_pk_fma_f32 v[158:159], v[122:123], v[158:159], v[108:109]
	v_pk_fma_f32 v[156:157], v[98:99], v[156:157], v[138:139]
	v_pk_mul_f32 v[108:109], v[124:125], v[106:107]
	v_pk_mul_f32 v[138:139], v[100:101], v[104:105]
	v_mfma_f32_16x16x16_bf16 v[146:149], v[128:129], v[164:165], v[146:149]
	v_mul_f32_e64 v104, v90, v104
	v_mul_f32_e64 v105, v91, v105
	v_mfma_f32_16x16x16_bf16 v[152:155], v[130:131], v[164:165], v[176:179]
	s_nop 2
	v_fma_f32 v178, v96, v182, -v108
	v_fma_f32 v179, v97, v183, -v109
	v_pk_fma_f32 v[176:177], v[90:91], v[180:181], v[138:139] neg_lo:[0,0,1] neg_hi:[0,0,1]
	v_pk_mul_f32 v[138:139], v[96:97], v[106:107]
	v_mfma_f32_16x16x16_bf16 v[172:175], v[126:127], v[164:165], v[172:175]
	v_mfma_f32_16x16x16_bf16 v[106:109], v[134:135], v[164:165], v[176:179]
	s_nop 2
	v_fma_f32 v178, v124, v182, v138
	v_fma_f32 v179, v125, v183, v139
	v_pk_fma_f32 v[176:177], v[100:101], v[180:181], v[104:105]
	v_pk_mul_f32 v[104:105], v[118:119], v[170:171]
	v_pk_mul_f32 v[138:139], v[88:89], v[168:169]
	v_mfma_f32_16x16x16_bf16 v[156:159], v[132:133], v[164:165], v[156:159]
	v_fma_f32 v182, v80, v142, -v104
	v_fma_f32 v183, v81, v143, -v105
	v_pk_fma_f32 v[180:181], v[78:79], v[140:141], v[138:139] neg_lo:[0,0,1] neg_hi:[0,0,1]
	v_pk_mul_f32 v[104:105], v[80:81], v[170:171]
	v_pk_mul_f32 v[138:139], v[78:79], v[168:169]
	v_pk_fma_f32 v[142:143], v[118:119], v[142:143], v[104:105]
	v_pk_fma_f32 v[140:141], v[88:89], v[140:141], v[138:139]
	v_mfma_f32_16x16x16_bf16 v[176:179], v[136:137], v[164:165], v[176:179]
	v_mul_f32_e64 v104, v120, v148
	v_mul_f32_e64 v105, v121, v149
	v_pk_fma_f32 v[170:171], v[86:87], v[174:175], v[104:105] neg_lo:[0,0,1] neg_hi:[0,0,1]
	v_mfma_f32_16x16x16_bf16 v[138:141], v[116:117], v[166:167], v[140:143]
	v_mul_f32_e64 v104, v86, v148
	v_mul_f32_e64 v105, v87, v149
	s_nop 0
	v_pk_mul_f32 v[142:143], v[94:95], v[146:147]
	v_mfma_f32_16x16x16_bf16 v[180:183], v[114:115], v[166:167], v[180:183]
	v_fma_f32 v168, v82, v172, -v142
	v_fma_f32 v169, v83, v173, -v143
	v_pk_mul_f32 v[142:143], v[82:83], v[146:147]
	s_nop 0
	v_mfma_f32_16x16x16_bf16 v[148:151], v[126:127], v[166:167], v[168:171]
	s_nop 2
	v_fma_f32 v170, v120, v174, v104
	v_fma_f32 v171, v121, v175, v105
	v_pk_fma_f32 v[168:169], v[94:95], v[172:173], v[142:143]
	v_pk_mul_f32 v[104:105], v[122:123], v[158:159]
	v_pk_mul_f32 v[142:143], v[98:99], v[156:157]
	v_pk_fma_f32 v[174:175], v[92:93], v[154:155], v[104:105] neg_lo:[0,0,1] neg_hi:[0,0,1]
	v_pk_fma_f32 v[172:173], v[84:85], v[152:153], v[142:143] neg_lo:[0,0,1] neg_hi:[0,0,1]
	v_pk_mul_f32 v[104:105], v[92:93], v[158:159]
	v_pk_mul_f32 v[142:143], v[84:85], v[156:157]
	v_pk_fma_f32 v[154:155], v[122:123], v[154:155], v[104:105]
	v_pk_fma_f32 v[152:153], v[98:99], v[152:153], v[142:143]
	v_pk_mul_f32 v[104:105], v[124:125], v[178:179]
	v_pk_mul_f32 v[142:143], v[100:101], v[176:177]
	v_pk_fma_f32 v[158:159], v[96:97], v[108:109], v[104:105] neg_lo:[0,0,1] neg_hi:[0,0,1]
	v_pk_fma_f32 v[156:157], v[90:91], v[106:107], v[142:143] neg_lo:[0,0,1] neg_hi:[0,0,1]
	v_pk_mul_f32 v[104:105], v[96:97], v[178:179]
	v_pk_mul_f32 v[142:143], v[90:91], v[176:177]
	v_pk_fma_f32 v[108:109], v[124:125], v[108:109], v[104:105]
	v_pk_fma_f32 v[106:107], v[100:101], v[106:107], v[142:143]
	v_mfma_f32_16x16x16_bf16 v[168:171], v[128:129], v[166:167], v[168:171]
	v_mul_f32_e64 v142, v88, v138
	v_mul_f32_e64 v143, v89, v139
	v_pk_mul_f32 v[138:139], v[78:79], v[138:139]
	v_pk_fma_f32 v[176:177], v[78:79], v[180:181], v[142:143] neg_lo:[0,0,1] neg_hi:[0,0,1]
	v_mfma_f32_16x16x16_bf16 v[172:175], v[130:131], v[166:167], v[172:175]
	v_mfma_f32_16x16x16_bf16 v[152:155], v[132:133], v[166:167], v[152:155]
	v_mfma_f32_16x16x16_bf16 v[156:159], v[134:135], v[166:167], v[156:159]
	v_mfma_f32_16x16x16_bf16 v[104:107], v[136:137], v[166:167], v[106:109]
	ds_read2_b64 v[164:167], v163 offset0:24 offset1:28
	s_nop 1
	v_pk_mul_f32 v[108:109], v[118:119], v[140:141]
	s_nop 0
	v_pk_fma_f32 v[178:179], v[80:81], v[182:183], v[108:109] neg_lo:[0,0,1] neg_hi:[0,0,1]
	v_pk_mul_f32 v[108:109], v[80:81], v[140:141]
	s_waitcnt lgkmcnt(0)
; #define LAS __attribute__((address_space(3)))
; #define S5_UPDATE(K, hre, him, xq) do { const v2u xb_ = (xq); \
;     _Pragma("unroll") for (int j = 0; j < 4; ++j) { const f32x4 cre_ = K.ar[j] * hre[j] - K.ai[j] * him[j], cim_ = K.ar[j] * him[j] + K.ai[j] * hre[j]; \
;         hre[j] = MFMA16K16(K.Bf[2 * j], xb_, cre_); him[j] = MFMA16K16(K.Bf[2 * j + 1], xb_, cim_); } } while (0)
; __device__ __forceinline__ void s5_prompt_task(const Args& a, const Ctx& C, int b, int g, v4u (&xv)[8]) {
;     ...
;     const LAS unsigned char* xsl = XS + chunk * 528 + q * 8;
;     for (int t = 0; t < 16; ++t) { const v2u xq = *(const LAS v2u*)(xsl + t * 32); S5_UPDATE(K, hre, him, xq); }
	v_mfma_f32_16x16x16_bf16 v[140:143], v[114:115], v[164:165], v[176:179]
	s_nop 2
	v_fma_f32 v176, v88, v180, v138
	v_fma_f32 v177, v89, v181, v139
	v_pk_mul_f32 v[138:139], v[94:95], v[168:169]
	v_pk_fma_f32 v[178:179], v[118:119], v[182:183], v[108:109]
	v_pk_mul_f32 v[108:109], v[120:121], v[170:171]
	v_pk_fma_f32 v[180:181], v[82:83], v[148:149], v[138:139] neg_lo:[0,0,1] neg_hi:[0,0,1]
	v_pk_mul_f32 v[138:139], v[82:83], v[168:169]
	v_mfma_f32_16x16x16_bf16 v[176:179], v[116:117], v[164:165], v[176:179]
	v_fma_f32 v182, v86, v150, -v108
	v_fma_f32 v183, v87, v151, -v109
	v_pk_mul_f32 v[108:109], v[86:87], v[170:171]
	v_pk_fma_f32 v[148:149], v[94:95], v[148:149], v[138:139]
	v_pk_mul_f32 v[138:139], v[98:99], v[152:153]
	v_pk_fma_f32 v[150:151], v[120:121], v[150:151], v[108:109]
	v_pk_mul_f32 v[108:109], v[122:123], v[154:155]
	v_pk_fma_f32 v[168:169], v[84:85], v[172:173], v[138:139] neg_lo:[0,0,1] neg_hi:[0,0,1]
	v_pk_mul_f32 v[138:139], v[84:85], v[152:153]
	v_mfma_f32_16x16x16_bf16 v[146:149], v[128:129], v[164:165], v[148:151]
	v_fma_f32 v170, v92, v174, -v108
	v_fma_f32 v171, v93, v175, -v109
	v_pk_mul_f32 v[108:109], v[92:93], v[154:155]
	v_pk_fma_f32 v[150:151], v[98:99], v[172:173], v[138:139]
	v_pk_mul_f32 v[138:139], v[100:101], v[104:105]
	v_pk_fma_f32 v[152:153], v[122:123], v[174:175], v[108:109]
	v_pk_mul_f32 v[108:109], v[124:125], v[106:107]
	v_pk_fma_f32 v[172:173], v[90:91], v[156:157], v[138:139] neg_lo:[0,0,1] neg_hi:[0,0,1]
	v_pk_mul_f32 v[138:139], v[96:97], v[106:107]
	v_pk_mul_f32 v[104:105], v[90:91], v[104:105]
	v_mfma_f32_16x16x16_bf16 v[180:183], v[126:127], v[164:165], v[180:183]
	v_fma_f32 v174, v96, v158, -v108
	v_fma_f32 v175, v97, v159, -v109
	v_pk_fma_f32 v[158:159], v[124:125], v[158:159], v[138:139]
	v_pk_fma_f32 v[156:157], v[100:101], v[156:157], v[104:105]
	v_pk_mul_f32 v[104:105], v[118:119], v[178:179]
	v_pk_mul_f32 v[138:139], v[88:89], v[176:177]
	v_mfma_f32_16x16x16_bf16 v[150:153], v[132:133], v[164:165], v[150:153]
	v_mfma_f32_16x16x16_bf16 v[106:109], v[134:135], v[164:165], v[172:175]
	s_nop 2
	v_fma_f32 v174, v80, v142, -v104
	v_fma_f32 v175, v81, v143, -v105
	v_pk_fma_f32 v[172:173], v[78:79], v[140:141], v[138:139] neg_lo:[0,0,1] neg_hi:[0,0,1]
	v_pk_mul_f32 v[104:105], v[80:81], v[178:179]
	v_pk_mul_f32 v[138:139], v[78:79], v[176:177]
	v_mfma_f32_16x16x16_bf16 v[168:171], v[130:131], v[164:165], v[168:171]
	v_fma_f32 v142, v118, v142, v104
	v_fma_f32 v143, v119, v143, v105
	v_pk_fma_f32 v[140:141], v[88:89], v[140:141], v[138:139]
	v_pk_mul_f32 v[104:105], v[120:121], v[148:149]
	v_mfma_f32_16x16x16_bf16 v[154:157], v[136:137], v[164:165], v[156:159]
	v_fma_f32 v178, v86, v182, -v104
	v_fma_f32 v179, v87, v183, -v105
	v_pk_mul_f32 v[104:105], v[86:87], v[148:149]
	v_mfma_f32_16x16x16_bf16 v[138:141], v[116:117], v[166:167], v[140:143]
	v_fma_f32 v148, v120, v182, v104
	v_fma_f32 v149, v121, v183, v105
	v_pk_mul_f32 v[104:105], v[122:123], v[152:153]
	v_pk_mul_f32 v[142:143], v[94:95], v[146:147]
	v_pk_fma_f32 v[182:183], v[92:93], v[170:171], v[104:105] neg_lo:[0,0,1] neg_hi:[0,0,1]
	v_pk_fma_f32 v[176:177], v[82:83], v[180:181], v[142:143] neg_lo:[0,0,1] neg_hi:[0,0,1]
	v_pk_mul_f32 v[142:143], v[82:83], v[146:147]
	v_pk_mul_f32 v[104:105], v[92:93], v[152:153]
	v_pk_fma_f32 v[146:147], v[94:95], v[180:181], v[142:143]
	v_pk_mul_f32 v[142:143], v[98:99], v[150:151]
	v_pk_fma_f32 v[152:153], v[122:123], v[170:171], v[104:105]
	v_pk_fma_f32 v[180:181], v[84:85], v[168:169], v[142:143] neg_lo:[0,0,1] neg_hi:[0,0,1]
	v_pk_mul_f32 v[142:143], v[84:85], v[150:151]
	v_pk_mul_f32 v[104:105], v[124:125], v[156:157]
	v_pk_fma_f32 v[150:151], v[98:99], v[168:169], v[142:143]
	v_pk_mul_f32 v[142:143], v[100:101], v[154:155]
	v_pk_fma_f32 v[170:171], v[96:97], v[108:109], v[104:105] neg_lo:[0,0,1] neg_hi:[0,0,1]
	v_pk_fma_f32 v[168:169], v[90:91], v[106:107], v[142:143] neg_lo:[0,0,1] neg_hi:[0,0,1]
	v_pk_mul_f32 v[104:105], v[96:97], v[156:157]
	v_pk_mul_f32 v[142:143], v[90:91], v[154:155]
	v_pk_fma_f32 v[108:109], v[124:125], v[108:109], v[104:105]
	v_pk_fma_f32 v[106:107], v[100:101], v[106:107], v[142:143]
	v_mfma_f32_16x16x16_bf16 v[172:175], v[114:115], v[166:167], v[172:175]
	v_mul_f32_e64 v142, v88, v138
	v_mul_f32_e64 v143, v89, v139
	v_pk_mul_f32 v[138:139], v[78:79], v[138:139]
	v_mfma_f32_16x16x16_bf16 v[176:179], v[126:127], v[166:167], v[176:179]
	v_mfma_f32_16x16x16_bf16 v[146:149], v[128:129], v[166:167], v[146:149]
	v_mfma_f32_16x16x16_bf16 v[180:183], v[130:131], v[166:167], v[180:183]
	v_mfma_f32_16x16x16_bf16 v[150:153], v[132:133], v[166:167], v[150:153]
	v_mfma_f32_16x16x16_bf16 v[156:159], v[134:135], v[166:167], v[168:171]
	v_mfma_f32_16x16x16_bf16 v[104:107], v[136:137], v[166:167], v[106:109]
	ds_read2_b64 v[164:167], v163 offset0:32 offset1:36
	s_nop 0
	v_pk_fma_f32 v[168:169], v[78:79], v[172:173], v[142:143] neg_lo:[0,0,1] neg_hi:[0,0,1]
	v_pk_mul_f32 v[108:109], v[118:119], v[140:141]
	s_nop 0
	v_pk_fma_f32 v[170:171], v[80:81], v[174:175], v[108:109] neg_lo:[0,0,1] neg_hi:[0,0,1]
	v_pk_mul_f32 v[108:109], v[80:81], v[140:141]
	s_waitcnt lgkmcnt(0)
; #define LAS __attribute__((address_space(3)))
; #define S5_UPDATE(K, hre, him, xq) do { const v2u xb_ = (xq); \
;     _Pragma("unroll") for (int j = 0; j < 4; ++j) { const f32x4 cre_ = K.ar[j] * hre[j] - K.ai[j] * him[j], cim_ = K.ar[j] * him[j] + K.ai[j] * hre[j]; \
;         hre[j] = MFMA16K16(K.Bf[2 * j], xb_, cre_); him[j] = MFMA16K16(K.Bf[2 * j + 1], xb_, cim_); } } while (0)
; __device__ __forceinline__ void s5_prompt_task(const Args& a, const Ctx& C, int b, int g, v4u (&xv)[8]) {
;     ...
;     const LAS unsigned char* xsl = XS + chunk * 528 + q * 8;
;     for (int t = 0; t < 16; ++t) { const v2u xq = *(const LAS v2u*)(xsl + t * 32); S5_UPDATE(K, hre, him, xq); }
	v_mfma_f32_16x16x16_bf16 v[140:143], v[114:115], v[164:165], v[168:171]
	s_nop 2
	v_fma_f32 v170, v118, v174, v108
	v_fma_f32 v171, v119, v175, v109
	v_pk_fma_f32 v[168:169], v[88:89], v[172:173], v[138:139]
	v_pk_mul_f32 v[108:109], v[120:121], v[148:149]
	v_pk_mul_f32 v[138:139], v[94:95], v[146:147]
	v_pk_fma_f32 v[174:175], v[86:87], v[178:179], v[108:109] neg_lo:[0,0,1] neg_hi:[0,0,1]
	v_pk_fma_f32 v[172:173], v[82:83], v[176:177], v[138:139] neg_lo:[0,0,1] neg_hi:[0,0,1]
	v_pk_mul_f32 v[108:109], v[86:87], v[148:149]
	v_pk_mul_f32 v[138:139], v[82:83], v[146:147]
	v_mfma_f32_16x16x16_bf16 v[168:171], v[116:117], v[164:165], v[168:171]
	v_fma_f32 v148, v120, v178, v108
	v_fma_f32 v149, v121, v179, v109
	v_pk_fma_f32 v[146:147], v[94:95], v[176:177], v[138:139]
	v_pk_mul_f32 v[108:109], v[122:123], v[152:153]
	v_pk_mul_f32 v[138:139], v[98:99], v[150:151]
	v_pk_fma_f32 v[178:179], v[92:93], v[182:183], v[108:109] neg_lo:[0,0,1] neg_hi:[0,0,1]
	v_pk_fma_f32 v[176:177], v[84:85], v[180:181], v[138:139] neg_lo:[0,0,1] neg_hi:[0,0,1]
	v_pk_mul_f32 v[138:139], v[84:85], v[150:151]
	v_pk_mul_f32 v[108:109], v[92:93], v[152:153]
	v_mfma_f32_16x16x16_bf16 v[152:155], v[130:131], v[164:165], v[176:179]
	s_nop 2
	v_fma_f32 v176, v98, v180, v138
	v_fma_f32 v177, v99, v181, v139
	v_pk_mul_f32 v[138:139], v[100:101], v[104:105]
	v_mfma_f32_16x16x16_bf16 v[146:149], v[128:129], v[164:165], v[146:149]
	v_fma_f32 v178, v122, v182, v108
	v_fma_f32 v179, v123, v183, v109
	v_pk_mul_f32 v[108:109], v[124:125], v[106:107]
	v_pk_fma_f32 v[180:181], v[90:91], v[156:157], v[138:139] neg_lo:[0,0,1] neg_hi:[0,0,1]
	v_pk_mul_f32 v[138:139], v[96:97], v[106:107]
	v_pk_mul_f32 v[104:105], v[90:91], v[104:105]
	v_mfma_f32_16x16x16_bf16 v[172:175], v[126:127], v[164:165], v[172:175]
	v_fma_f32 v182, v96, v158, -v108
	v_fma_f32 v183, v97, v159, -v109
	v_pk_fma_f32 v[158:159], v[124:125], v[158:159], v[138:139]
	v_pk_fma_f32 v[156:157], v[100:101], v[156:157], v[104:105]
	v_pk_mul_f32 v[104:105], v[118:119], v[170:171]
	v_pk_mul_f32 v[138:139], v[88:89], v[168:169]
	v_mfma_f32_16x16x16_bf16 v[176:179], v[132:133], v[164:165], v[176:179]
	v_mfma_f32_16x16x16_bf16 v[106:109], v[134:135], v[164:165], v[180:183]
	s_nop 2
	v_fma_f32 v182, v80, v142, -v104
	v_fma_f32 v183, v81, v143, -v105
	v_pk_fma_f32 v[180:181], v[78:79], v[140:141], v[138:139] neg_lo:[0,0,1] neg_hi:[0,0,1]
	v_pk_mul_f32 v[104:105], v[80:81], v[170:171]
	v_pk_mul_f32 v[138:139], v[78:79], v[168:169]
	v_pk_fma_f32 v[142:143], v[118:119], v[142:143], v[104:105]
	v_pk_fma_f32 v[140:141], v[88:89], v[140:141], v[138:139]
	v_mfma_f32_16x16x16_bf16 v[156:159], v[136:137], v[164:165], v[156:159]
	v_mul_f32_e64 v104, v120, v148
	v_mul_f32_e64 v105, v121, v149
	v_pk_fma_f32 v[170:171], v[86:87], v[174:175], v[104:105] neg_lo:[0,0,1] neg_hi:[0,0,1]
	v_mfma_f32_16x16x16_bf16 v[138:141], v[116:117], v[166:167], v[140:143]
	v_mul_f32_e64 v104, v86, v148
	v_mul_f32_e64 v105, v87, v149
	s_nop 0
	v_pk_mul_f32 v[142:143], v[94:95], v[146:147]
	v_mfma_f32_16x16x16_bf16 v[180:183], v[114:115], v[166:167], v[180:183]
	v_fma_f32 v168, v82, v172, -v142
	v_fma_f32 v169, v83, v173, -v143
	v_pk_mul_f32 v[142:143], v[82:83], v[146:147]
	s_nop 0
	v_mfma_f32_16x16x16_bf16 v[148:151], v[126:127], v[166:167], v[168:171]
	s_nop 2
	v_fma_f32 v170, v120, v174, v104
	v_fma_f32 v171, v121, v175, v105
	v_pk_fma_f32 v[168:169], v[94:95], v[172:173], v[142:143]
	v_pk_mul_f32 v[104:105], v[122:123], v[178:179]
	v_pk_mul_f32 v[142:143], v[98:99], v[176:177]
	v_pk_fma_f32 v[174:175], v[92:93], v[154:155], v[104:105] neg_lo:[0,0,1] neg_hi:[0,0,1]
	v_pk_fma_f32 v[172:173], v[84:85], v[152:153], v[142:143] neg_lo:[0,0,1] neg_hi:[0,0,1]
	v_pk_mul_f32 v[104:105], v[92:93], v[178:179]
	v_pk_mul_f32 v[142:143], v[84:85], v[176:177]
	v_pk_fma_f32 v[154:155], v[122:123], v[154:155], v[104:105]
	v_pk_fma_f32 v[152:153], v[98:99], v[152:153], v[142:143]
	v_pk_mul_f32 v[104:105], v[124:125], v[158:159]
	v_pk_mul_f32 v[142:143], v[100:101], v[156:157]
	v_pk_fma_f32 v[178:179], v[96:97], v[108:109], v[104:105] neg_lo:[0,0,1] neg_hi:[0,0,1]
	v_pk_fma_f32 v[176:177], v[90:91], v[106:107], v[142:143] neg_lo:[0,0,1] neg_hi:[0,0,1]
	v_pk_mul_f32 v[104:105], v[96:97], v[158:159]
	v_pk_mul_f32 v[142:143], v[90:91], v[156:157]
	ds_read2_b64 v[156:159], v163 offset0:40 offset1:44
	v_mfma_f32_16x16x16_bf16 v[168:171], v[128:129], v[166:167], v[168:171]
	v_fma_f32 v108, v124, v108, v104
	v_fma_f32 v109, v125, v109, v105
	v_pk_fma_f32 v[106:107], v[100:101], v[106:107], v[142:143]
	v_pk_mul_f32 v[142:143], v[88:89], v[138:139]
	v_mfma_f32_16x16x16_bf16 v[152:155], v[132:133], v[166:167], v[152:155]
	v_fma_f32 v164, v78, v180, -v142
	v_fma_f32 v165, v79, v181, -v143
	v_pk_mul_f32 v[138:139], v[78:79], v[138:139]
	v_mfma_f32_16x16x16_bf16 v[104:107], v[136:137], v[166:167], v[106:109]
	s_nop 2
	v_mul_f32_e64 v108, v118, v140
	v_mul_f32_e64 v109, v119, v141
	v_mfma_f32_16x16x16_bf16 v[172:175], v[130:131], v[166:167], v[172:175]
	v_mfma_f32_16x16x16_bf16 v[176:179], v[134:135], v[166:167], v[176:179]
	v_fma_f32 v166, v80, v182, -v108
	v_fma_f32 v167, v81, v183, -v109
	v_pk_mul_f32 v[108:109], v[80:81], v[140:141]
	s_waitcnt lgkmcnt(0)
; #define LAS __attribute__((address_space(3)))
; #define S5_UPDATE(K, hre, him, xq) do { const v2u xb_ = (xq); \
;     _Pragma("unroll") for (int j = 0; j < 4; ++j) { const f32x4 cre_ = K.ar[j] * hre[j] - K.ai[j] * him[j], cim_ = K.ar[j] * him[j] + K.ai[j] * hre[j]; \
;         hre[j] = MFMA16K16(K.Bf[2 * j], xb_, cre_); him[j] = MFMA16K16(K.Bf[2 * j + 1], xb_, cim_); } } while (0)
; __device__ __forceinline__ void s5_prompt_task(const Args& a, const Ctx& C, int b, int g, v4u (&xv)[8]) {
;     ...
;     const LAS unsigned char* xsl = XS + chunk * 528 + q * 8;
;     for (int t = 0; t < 16; ++t) { const v2u xq = *(const LAS v2u*)(xsl + t * 32); S5_UPDATE(K, hre, him, xq); }
	v_mfma_f32_16x16x16_bf16 v[140:143], v[114:115], v[156:157], v[164:167]
	s_nop 2
	v_fma_f32 v166, v118, v182, v108
	v_fma_f32 v167, v119, v183, v109
	v_pk_fma_f32 v[164:165], v[88:89], v[180:181], v[138:139]
	v_pk_mul_f32 v[108:109], v[120:121], v[170:171]
	v_pk_mul_f32 v[138:139], v[94:95], v[168:169]
	v_pk_fma_f32 v[182:183], v[86:87], v[150:151], v[108:109] neg_lo:[0,0,1] neg_hi:[0,0,1]
	v_pk_fma_f32 v[180:181], v[82:83], v[148:149], v[138:139] neg_lo:[0,0,1] neg_hi:[0,0,1]
	v_pk_mul_f32 v[108:109], v[86:87], v[170:171]
	v_pk_mul_f32 v[138:139], v[82:83], v[168:169]
	v_mfma_f32_16x16x16_bf16 v[164:167], v[116:117], v[156:157], v[164:167]
	v_fma_f32 v150, v120, v150, v108
	v_fma_f32 v151, v121, v151, v109
	v_pk_fma_f32 v[148:149], v[94:95], v[148:149], v[138:139]
	v_pk_mul_f32 v[108:109], v[122:123], v[154:155]
	v_pk_mul_f32 v[138:139], v[98:99], v[152:153]
	v_pk_fma_f32 v[170:171], v[92:93], v[174:175], v[108:109] neg_lo:[0,0,1] neg_hi:[0,0,1]
	v_pk_fma_f32 v[168:169], v[84:85], v[172:173], v[138:139] neg_lo:[0,0,1] neg_hi:[0,0,1]
	v_pk_mul_f32 v[108:109], v[92:93], v[154:155]
	v_pk_mul_f32 v[138:139], v[84:85], v[152:153]
	v_mfma_f32_16x16x16_bf16 v[146:149], v[128:129], v[156:157], v[148:151]
	v_fma_f32 v152, v122, v174, v108
	v_fma_f32 v153, v123, v175, v109
	v_pk_mul_f32 v[108:109], v[124:125], v[106:107]
	v_pk_fma_f32 v[150:151], v[98:99], v[172:173], v[138:139]
	v_pk_mul_f32 v[138:139], v[100:101], v[104:105]
	v_pk_fma_f32 v[174:175], v[96:97], v[178:179], v[108:109] neg_lo:[0,0,1] neg_hi:[0,0,1]
	v_pk_fma_f32 v[172:173], v[90:91], v[176:177], v[138:139] neg_lo:[0,0,1] neg_hi:[0,0,1]
	v_pk_mul_f32 v[138:139], v[96:97], v[106:107]
	v_pk_mul_f32 v[104:105], v[90:91], v[104:105]
	v_mfma_f32_16x16x16_bf16 v[180:183], v[126:127], v[156:157], v[180:183]
	v_mfma_f32_16x16x16_bf16 v[106:109], v[134:135], v[156:157], v[172:175]
	s_nop 2
	v_fma_f32 v174, v124, v178, v138
	v_fma_f32 v175, v125, v179, v139
	v_pk_fma_f32 v[172:173], v[100:101], v[176:177], v[104:105]
	v_pk_mul_f32 v[104:105], v[118:119], v[166:167]
	v_pk_mul_f32 v[138:139], v[88:89], v[164:165]
	v_mfma_f32_16x16x16_bf16 v[168:171], v[130:131], v[156:157], v[168:171]
	v_mfma_f32_16x16x16_bf16 v[150:153], v[132:133], v[156:157], v[150:153]
	v_mfma_f32_16x16x16_bf16 v[154:157], v[136:137], v[156:157], v[172:175]
	s_nop 2
	v_fma_f32 v174, v80, v142, -v104
	v_fma_f32 v175, v81, v143, -v105
	v_pk_fma_f32 v[172:173], v[78:79], v[140:141], v[138:139] neg_lo:[0,0,1] neg_hi:[0,0,1]
	v_pk_mul_f32 v[104:105], v[80:81], v[166:167]
	v_pk_mul_f32 v[138:139], v[78:79], v[164:165]
	v_pk_fma_f32 v[142:143], v[118:119], v[142:143], v[104:105]
	v_pk_fma_f32 v[140:141], v[88:89], v[140:141], v[138:139]
	v_pk_mul_f32 v[104:105], v[120:121], v[148:149]
	v_mfma_f32_16x16x16_bf16 v[172:175], v[114:115], v[158:159], v[172:175]
	v_fma_f32 v166, v86, v182, -v104
	v_fma_f32 v167, v87, v183, -v105
	v_pk_mul_f32 v[104:105], v[86:87], v[148:149]
	v_mfma_f32_16x16x16_bf16 v[138:141], v[116:117], v[158:159], v[140:143]
	v_fma_f32 v148, v120, v182, v104
	v_fma_f32 v149, v121, v183, v105
	v_pk_mul_f32 v[104:105], v[122:123], v[152:153]
	v_pk_mul_f32 v[142:143], v[94:95], v[146:147]
	v_pk_fma_f32 v[178:179], v[92:93], v[170:171], v[104:105] neg_lo:[0,0,1] neg_hi:[0,0,1]
	v_pk_fma_f32 v[164:165], v[82:83], v[180:181], v[142:143] neg_lo:[0,0,1] neg_hi:[0,0,1]
	v_pk_mul_f32 v[142:143], v[82:83], v[146:147]
	v_pk_mul_f32 v[104:105], v[92:93], v[152:153]
	v_pk_fma_f32 v[146:147], v[94:95], v[180:181], v[142:143]
	v_pk_mul_f32 v[142:143], v[98:99], v[150:151]
	v_pk_fma_f32 v[152:153], v[122:123], v[170:171], v[104:105]
	v_pk_fma_f32 v[176:177], v[84:85], v[168:169], v[142:143] neg_lo:[0,0,1] neg_hi:[0,0,1]
	v_pk_mul_f32 v[142:143], v[84:85], v[150:151]
	v_pk_mul_f32 v[104:105], v[124:125], v[156:157]
	v_pk_fma_f32 v[150:151], v[98:99], v[168:169], v[142:143]
	v_pk_mul_f32 v[142:143], v[100:101], v[154:155]
	v_mfma_f32_16x16x16_bf16 v[146:149], v[128:129], v[158:159], v[146:149]
	v_fma_f32 v170, v96, v108, -v104
	v_fma_f32 v171, v97, v109, -v105
	v_pk_fma_f32 v[168:169], v[90:91], v[106:107], v[142:143] neg_lo:[0,0,1] neg_hi:[0,0,1]
	v_pk_mul_f32 v[104:105], v[96:97], v[156:157]
	v_pk_mul_f32 v[142:143], v[90:91], v[154:155]
	ds_read2_b64 v[154:157], v163 offset0:48 offset1:52
	v_mfma_f32_16x16x16_bf16 v[164:167], v[126:127], v[158:159], v[164:167]
	v_fma_f32 v108, v124, v108, v104
	v_fma_f32 v109, v125, v109, v105
	v_pk_fma_f32 v[106:107], v[100:101], v[106:107], v[142:143]
	v_pk_mul_f32 v[142:143], v[88:89], v[138:139]
	v_mfma_f32_16x16x16_bf16 v[150:153], v[132:133], v[158:159], v[150:153]
	v_mul_f32_e64 v138, v78, v138
	v_mul_f32_e64 v139, v79, v139
	v_pk_fma_f32 v[180:181], v[78:79], v[172:173], v[142:143] neg_lo:[0,0,1] neg_hi:[0,0,1]
	v_pk_fma_f32 v[172:173], v[88:89], v[172:173], v[138:139]
	v_mfma_f32_16x16x16_bf16 v[176:179], v[130:131], v[158:159], v[176:179]
	v_mul_f32_e64 v138, v94, v146
	v_mul_f32_e64 v139, v95, v147
	v_mfma_f32_16x16x16_bf16 v[104:107], v[136:137], v[158:159], v[106:109]
	s_nop 2
	v_mul_f32_e64 v108, v118, v140
	v_mul_f32_e64 v109, v119, v141
	v_mfma_f32_16x16x16_bf16 v[168:171], v[134:135], v[158:159], v[168:171]
	v_fma_f32 v182, v80, v174, -v108
	v_fma_f32 v183, v81, v175, -v109
	v_pk_mul_f32 v[108:109], v[80:81], v[140:141]
	s_waitcnt lgkmcnt(0)
; #define LAS __attribute__((address_space(3)))
; #define S5_UPDATE(K, hre, him, xq) do { const v2u xb_ = (xq); \
;     _Pragma("unroll") for (int j = 0; j < 4; ++j) { const f32x4 cre_ = K.ar[j] * hre[j] - K.ai[j] * him[j], cim_ = K.ar[j] * him[j] + K.ai[j] * hre[j]; \
;         hre[j] = MFMA16K16(K.Bf[2 * j], xb_, cre_); him[j] = MFMA16K16(K.Bf[2 * j + 1], xb_, cim_); } } while (0)
; __device__ __forceinline__ void s5_prompt_task(const Args& a, const Ctx& C, int b, int g, v4u (&xv)[8]) {
;     ...
;     const LAS unsigned char* xsl = XS + chunk * 528 + q * 8;
;     for (int t = 0; t < 16; ++t) { const v2u xq = *(const LAS v2u*)(xsl + t * 32); S5_UPDATE(K, hre, him, xq); }
	v_mfma_f32_16x16x16_bf16 v[140:143], v[114:115], v[154:155], v[180:183]
	v_fma_f32 v174, v118, v174, v108
	v_fma_f32 v175, v119, v175, v109
	v_pk_mul_f32 v[108:109], v[120:121], v[148:149]
	v_pk_fma_f32 v[180:181], v[82:83], v[164:165], v[138:139] neg_lo:[0,0,1] neg_hi:[0,0,1]
	v_pk_mul_f32 v[138:139], v[82:83], v[146:147]
	v_mfma_f32_16x16x16_bf16 v[172:175], v[116:117], v[154:155], v[172:175]
	v_fma_f32 v182, v86, v166, -v108
	v_fma_f32 v183, v87, v167, -v109
	v_pk_mul_f32 v[108:109], v[86:87], v[148:149]
	v_pk_fma_f32 v[146:147], v[94:95], v[164:165], v[138:139]
	v_pk_mul_f32 v[138:139], v[98:99], v[150:151]
	v_pk_fma_f32 v[148:149], v[120:121], v[166:167], v[108:109]
	v_pk_mul_f32 v[108:109], v[122:123], v[152:153]
	v_pk_fma_f32 v[164:165], v[84:85], v[176:177], v[138:139] neg_lo:[0,0,1] neg_hi:[0,0,1]
	v_pk_mul_f32 v[138:139], v[84:85], v[150:151]
	v_pk_fma_f32 v[166:167], v[92:93], v[178:179], v[108:109] neg_lo:[0,0,1] neg_hi:[0,0,1]
	v_pk_mul_f32 v[108:109], v[92:93], v[152:153]
	v_pk_fma_f32 v[150:151], v[98:99], v[176:177], v[138:139]
	v_pk_mul_f32 v[138:139], v[100:101], v[104:105]
	v_mfma_f32_16x16x16_bf16 v[146:149], v[128:129], v[154:155], v[146:149]
	v_fma_f32 v152, v122, v178, v108
	v_fma_f32 v153, v123, v179, v109
	v_pk_mul_f32 v[108:109], v[124:125], v[106:107]
	v_pk_fma_f32 v[176:177], v[90:91], v[168:169], v[138:139] neg_lo:[0,0,1] neg_hi:[0,0,1]
	v_pk_mul_f32 v[138:139], v[96:97], v[106:107]
	v_pk_mul_f32 v[104:105], v[90:91], v[104:105]
	v_mfma_f32_16x16x16_bf16 v[180:183], v[126:127], v[154:155], v[180:183]
	v_fma_f32 v178, v96, v170, -v108
	v_fma_f32 v179, v97, v171, -v109
	v_pk_fma_f32 v[170:171], v[124:125], v[170:171], v[138:139]
	v_pk_fma_f32 v[168:169], v[100:101], v[168:169], v[104:105]
	v_pk_mul_f32 v[104:105], v[118:119], v[174:175]
	v_pk_mul_f32 v[138:139], v[88:89], v[172:173]
	v_mfma_f32_16x16x16_bf16 v[150:153], v[132:133], v[154:155], v[150:153]
	v_mfma_f32_16x16x16_bf16 v[106:109], v[134:135], v[154:155], v[176:179]
	s_nop 2
	v_fma_f32 v178, v80, v142, -v104
	v_fma_f32 v179, v81, v143, -v105
	v_pk_fma_f32 v[176:177], v[78:79], v[140:141], v[138:139] neg_lo:[0,0,1] neg_hi:[0,0,1]
	v_pk_mul_f32 v[104:105], v[80:81], v[174:175]
	v_pk_mul_f32 v[138:139], v[78:79], v[172:173]
	v_mfma_f32_16x16x16_bf16 v[164:167], v[130:131], v[154:155], v[164:167]
	v_fma_f32 v142, v118, v142, v104
	v_fma_f32 v143, v119, v143, v105
	v_pk_fma_f32 v[140:141], v[88:89], v[140:141], v[138:139]
	v_pk_mul_f32 v[104:105], v[120:121], v[148:149]
	v_mfma_f32_16x16x16_bf16 v[168:171], v[136:137], v[154:155], v[168:171]
	v_fma_f32 v186, v86, v182, -v104
	v_fma_f32 v187, v87, v183, -v105
	v_pk_mul_f32 v[104:105], v[86:87], v[148:149]
	v_mfma_f32_16x16x16_bf16 v[138:141], v[116:117], v[156:157], v[140:143]
	v_fma_f32 v148, v120, v182, v104
	v_fma_f32 v149, v121, v183, v105
	v_pk_mul_f32 v[104:105], v[122:123], v[152:153]
	v_pk_mul_f32 v[142:143], v[94:95], v[146:147]
	v_mfma_f32_16x16x16_bf16 v[174:177], v[114:115], v[156:157], v[176:179]
	v_fma_f32 v184, v82, v180, -v142
	v_fma_f32 v185, v83, v181, -v143
	v_pk_mul_f32 v[142:143], v[82:83], v[146:147]
	s_nop 0
	v_pk_fma_f32 v[146:147], v[94:95], v[180:181], v[142:143]
	v_pk_mul_f32 v[142:143], v[98:99], v[150:151]
	v_pk_fma_f32 v[180:181], v[92:93], v[166:167], v[104:105] neg_lo:[0,0,1] neg_hi:[0,0,1]
	v_pk_fma_f32 v[178:179], v[84:85], v[164:165], v[142:143] neg_lo:[0,0,1] neg_hi:[0,0,1]
	v_pk_mul_f32 v[104:105], v[92:93], v[152:153]
	v_pk_mul_f32 v[142:143], v[84:85], v[150:151]
	v_pk_fma_f32 v[166:167], v[122:123], v[166:167], v[104:105]
	v_pk_fma_f32 v[164:165], v[98:99], v[164:165], v[142:143]
	v_pk_mul_f32 v[104:105], v[124:125], v[170:171]
	v_pk_mul_f32 v[142:143], v[100:101], v[168:169]
	v_mfma_f32_16x16x16_bf16 v[152:155], v[130:131], v[156:157], v[178:181]
	s_nop 2
	v_fma_f32 v180, v96, v108, -v104
	v_fma_f32 v181, v97, v109, -v105
	v_pk_fma_f32 v[178:179], v[90:91], v[106:107], v[142:143] neg_lo:[0,0,1] neg_hi:[0,0,1]
	v_pk_mul_f32 v[104:105], v[96:97], v[170:171]
	v_pk_mul_f32 v[142:143], v[90:91], v[168:169]
	v_pk_fma_f32 v[108:109], v[124:125], v[108:109], v[104:105]
	v_pk_fma_f32 v[106:107], v[100:101], v[106:107], v[142:143]
	v_mfma_f32_16x16x16_bf16 v[184:187], v[126:127], v[156:157], v[184:187]
	v_mul_f32_e64 v142, v88, v138
	v_mul_f32_e64 v143, v89, v139
	v_pk_mul_f32 v[138:139], v[78:79], v[138:139]
	v_mfma_f32_16x16x16_bf16 v[146:149], v[128:129], v[156:157], v[146:149]
	v_mfma_f32_16x16x16_bf16 v[164:167], v[132:133], v[156:157], v[164:167]
	v_mfma_f32_16x16x16_bf16 v[170:173], v[134:135], v[156:157], v[178:181]
	v_mfma_f32_16x16x16_bf16 v[104:107], v[136:137], v[156:157], v[106:109]
	ds_read2_b64 v[156:159], v163 offset0:56 offset1:60
	s_nop 0
	v_pk_fma_f32 v[178:179], v[78:79], v[174:175], v[142:143] neg_lo:[0,0,1] neg_hi:[0,0,1]
	v_pk_fma_f32 v[174:175], v[88:89], v[174:175], v[138:139]
	v_pk_mul_f32 v[108:109], v[118:119], v[140:141]
	v_pk_mul_f32 v[138:139], v[94:95], v[146:147]
	v_pk_fma_f32 v[180:181], v[80:81], v[176:177], v[108:109] neg_lo:[0,0,1] neg_hi:[0,0,1]
	v_pk_mul_f32 v[108:109], v[80:81], v[140:141]
	s_nop 0
	v_pk_fma_f32 v[176:177], v[118:119], v[176:177], v[108:109]
	v_pk_mul_f32 v[108:109], v[120:121], v[148:149]
	s_waitcnt lgkmcnt(0)
; #define LAS __attribute__((address_space(3)))
; #define S5_UPDATE(K, hre, him, xq) do { const v2u xb_ = (xq); \
;     _Pragma("unroll") for (int j = 0; j < 4; ++j) { const f32x4 cre_ = K.ar[j] * hre[j] - K.ai[j] * him[j], cim_ = K.ar[j] * him[j] + K.ai[j] * hre[j]; \
;         hre[j] = MFMA16K16(K.Bf[2 * j], xb_, cre_); him[j] = MFMA16K16(K.Bf[2 * j + 1], xb_, cim_); } } while (0)
; __device__ __forceinline__ void s5_prompt_task(const Args& a, const Ctx& C, int b, int g, v4u (&xv)[8]) {
;     ...
;     for (int t = 0; t < 16; ++t) { const v2u xq = *(const LAS v2u*)(xsl + t * 32); S5_UPDATE(K, hre, him, xq); }
; #pragma unroll
;     for (int j = 0; j < 4; ++j) { LAS float* d = SH + chunk * 132 + 2 * (16 * j + 4 * q);
;         *(LAS f32x4*)d = (f32x4){hre[j][0], him[j][0], hre[j][1], him[j][1]}; *(LAS f32x4*)(d + 4) = (f32x4){hre[j][2], him[j][2], hre[j][3], him[j][3]}; }
;     v2u zq[4];
; #pragma unroll
;     for (int t = 0; t < 4; ++t) zq[t] = __builtin_nontemporal_load((const v2u*)(ZBg + (size_t)(16 * chunk + t) * 16 + 4 * q));
	v_mfma_f32_16x16x16_bf16 v[140:143], v[114:115], v[156:157], v[178:181]
	s_nop 2
	v_fma_f32 v180, v86, v186, -v108
	v_fma_f32 v181, v87, v187, -v109
	v_pk_fma_f32 v[178:179], v[82:83], v[184:185], v[138:139] neg_lo:[0,0,1] neg_hi:[0,0,1]
	v_pk_mul_f32 v[138:139], v[82:83], v[146:147]
	v_mfma_f32_16x16x16_bf16 v[174:177], v[116:117], v[156:157], v[174:177]
	v_mul_f32_e64 v108, v86, v148
	v_mul_f32_e64 v109, v87, v149
	v_mfma_f32_16x16x16_bf16 v[148:151], v[126:127], v[156:157], v[178:181]
	s_nop 2
	v_fma_f32 v178, v94, v184, v138
	v_fma_f32 v179, v95, v185, v139
	v_pk_mul_f32 v[138:139], v[98:99], v[164:165]
	v_pk_fma_f32 v[180:181], v[120:121], v[186:187], v[108:109]
	v_pk_mul_f32 v[108:109], v[122:123], v[166:167]
	v_pk_fma_f32 v[182:183], v[84:85], v[152:153], v[138:139] neg_lo:[0,0,1] neg_hi:[0,0,1]
	v_pk_mul_f32 v[138:139], v[84:85], v[164:165]
	v_mfma_f32_16x16x16_bf16 v[178:181], v[128:129], v[156:157], v[178:181]
	v_fma_f32 v184, v92, v154, -v108
	v_fma_f32 v185, v93, v155, -v109
	v_pk_mul_f32 v[108:109], v[92:93], v[166:167]
	v_pk_fma_f32 v[152:153], v[98:99], v[152:153], v[138:139]
	v_pk_mul_f32 v[138:139], v[100:101], v[104:105]
	v_mfma_f32_16x16x16_bf16 v[166:169], v[130:131], v[156:157], v[182:185]
	v_fma_f32 v154, v122, v154, v108
	v_fma_f32 v155, v123, v155, v109
	v_pk_mul_f32 v[108:109], v[124:125], v[106:107]
	v_pk_mul_f32 v[104:105], v[90:91], v[104:105]
	v_pk_fma_f32 v[182:183], v[90:91], v[170:171], v[138:139] neg_lo:[0,0,1] neg_hi:[0,0,1]
	v_pk_mul_f32 v[138:139], v[96:97], v[106:107]
	v_mfma_f32_16x16x16_bf16 v[152:155], v[132:133], v[156:157], v[152:155]
	v_fma_f32 v184, v96, v172, -v108
	v_fma_f32 v185, v97, v173, -v109
	v_pk_fma_f32 v[172:173], v[124:125], v[172:173], v[138:139]
	v_pk_mul_f32 v[138:139], v[88:89], v[174:175]
	v_mfma_f32_16x16x16_bf16 v[106:109], v[134:135], v[156:157], v[182:185]
	v_fma_f32 v170, v100, v170, v104
	v_fma_f32 v171, v101, v171, v105
	v_pk_mul_f32 v[104:105], v[118:119], v[176:177]
	v_pk_fma_f32 v[182:183], v[78:79], v[140:141], v[138:139] neg_lo:[0,0,1] neg_hi:[0,0,1]
	v_pk_mul_f32 v[78:79], v[78:79], v[174:175]
	v_mfma_f32_16x16x16_bf16 v[170:173], v[136:137], v[156:157], v[170:173]
	v_fma_f32 v184, v80, v142, -v104
	v_fma_f32 v185, v81, v143, -v105
	v_pk_fma_f32 v[78:79], v[88:89], v[140:141], v[78:79]
	v_pk_mul_f32 v[88:89], v[120:121], v[180:181]
	v_pk_mul_f32 v[104:105], v[94:95], v[178:179]
	v_pk_fma_f32 v[140:141], v[86:87], v[150:151], v[88:89] neg_lo:[0,0,1] neg_hi:[0,0,1]
	v_pk_fma_f32 v[138:139], v[82:83], v[148:149], v[104:105] neg_lo:[0,0,1] neg_hi:[0,0,1]
	v_pk_mul_f32 v[82:83], v[82:83], v[178:179]
	v_pk_mul_f32 v[80:81], v[80:81], v[176:177]
	v_pk_mul_f32 v[104:105], v[86:87], v[180:181]
	v_mfma_f32_16x16x16_bf16 v[86:89], v[126:127], v[158:159], v[138:141]
	v_fma_f32 v80, v118, v142, v80
	v_fma_f32 v81, v119, v143, v81
	s_nop 0
	v_pk_fma_f32 v[138:139], v[94:95], v[148:149], v[82:83]
	v_pk_mul_f32 v[82:83], v[122:123], v[154:155]
	v_pk_fma_f32 v[140:141], v[120:121], v[150:151], v[104:105]
	v_pk_mul_f32 v[94:95], v[98:99], v[152:153]
	v_pk_fma_f32 v[148:149], v[92:93], v[168:169], v[82:83] neg_lo:[0,0,1] neg_hi:[0,0,1]
	v_pk_mul_f32 v[82:83], v[92:93], v[154:155]
	v_pk_mul_f32 v[104:105], v[84:85], v[152:153]
	v_mfma_f32_16x16x16_bf16 v[182:185], v[114:115], v[158:159], v[182:185]
	v_fma_f32 v146, v84, v166, -v94
	v_fma_f32 v147, v85, v167, -v95
	v_pk_fma_f32 v[84:85], v[122:123], v[168:169], v[82:83]
	v_pk_fma_f32 v[82:83], v[98:99], v[166:167], v[104:105]
	v_mfma_f32_16x16x16_bf16 v[78:81], v[116:117], v[158:159], v[78:81]
	v_mul_f32_e64 v104, v100, v170
	v_mul_f32_e64 v105, v101, v171
	v_pk_mul_f32 v[98:99], v[124:125], v[172:173]
	v_mov_b32_e32 v102, v183
	v_mfma_f32_16x16x16_bf16 v[138:141], v[128:129], v[158:159], v[138:141]
	v_lshlrev_b32_e32 v152, 3, v162
	s_nop 1
	v_mov_b32_e32 v103, v79
	v_mov_b32_e32 v79, v80
	v_mfma_f32_16x16x16_bf16 v[92:95], v[130:131], v[158:159], v[146:149]
	v_mov_b32_e32 v80, v185
	v_mov_b32_e32 v153, v111
	s_nop 0
	v_pk_fma_f32 v[146:147], v[90:91], v[106:107], v[104:105] neg_lo:[0,0,1] neg_hi:[0,0,1]
	v_pk_mul_f32 v[104:105], v[96:97], v[172:173]
	v_pk_mul_f32 v[90:91], v[90:91], v[170:171]
	v_mfma_f32_16x16x16_bf16 v[82:85], v[132:133], v[158:159], v[82:85]
	v_fma_f32 v148, v96, v108, -v98
	v_fma_f32 v149, v97, v109, -v99
	v_pk_fma_f32 v[108:109], v[124:125], v[108:109], v[104:105]
	v_pk_fma_f32 v[106:107], v[100:101], v[106:107], v[90:91]
	v_mfma_f32_16x16x16_bf16 v[96:99], v[134:135], v[158:159], v[146:149]
	v_mov_b32_e32 v101, v78
	v_mov_b32_e32 v78, v184
	ds_write_b128 v3, v[78:81] offset:16
	v_mfma_f32_16x16x16_bf16 v[104:107], v[136:137], v[158:159], v[106:109]
	v_mov_b32_e32 v78, v86
	v_mov_b32_e32 v79, v138
	v_mov_b32_e32 v80, v87
	v_mov_b32_e32 v81, v139
	ds_write_b128 v3, v[78:81] offset:128
	v_mov_b32_e32 v78, v92
	v_mov_b32_e32 v79, v82
	v_mov_b32_e32 v80, v93
	v_mov_b32_e32 v81, v83
	ds_write_b128 v3, v[78:81] offset:256
	v_mov_b32_e32 v78, v96
	v_mov_b32_e32 v79, v104
	v_mov_b32_e32 v80, v97
	v_mov_b32_e32 v81, v105
	v_mov_b32_e32 v138, v88
	v_mov_b32_e32 v139, v140
	v_mov_b32_e32 v140, v89
	v_mov_b32_e32 v82, v94
	v_mov_b32_e32 v83, v84
	v_mov_b32_e32 v84, v95
	ds_write_b128 v3, v[78:81] offset:384
	v_lshl_add_u64 v[78:79], s[4:5], 0, v[110:111]
	s_mov_b64 s[4:5], 0xd400000
	v_mov_b32_e32 v110, v7
	v_mov_b32_e32 v100, v182
	ds_write_b128 v3, v[138:141] offset:144
	ds_write_b128 v3, v[82:85] offset:272
	v_mov_b32_e32 v104, v98
	v_mov_b32_e32 v105, v106
	v_mov_b32_e32 v106, v99
	v_lshl_add_u64 v[138:139], v[78:79], 0, s[4:5]
	v_lshlrev_b64 v[78:79], 5, v[110:111]
	v_or_b32_e32 v80, 1, v7
	v_mov_b32_e32 v81, v111
; #define LAS __attribute__((address_space(3)))
; #define LDS_WAIT() asm volatile("s_waitcnt lgkmcnt(0)" ::: "memory")
; __device__ __forceinline__ bf16x8 pack8(f32x4 lo, f32x4 hi) { v4u w; w.x = pk2(lo[0], lo[1]); w.y = pk2(lo[2], lo[3]); w.z = pk2(hi[0], hi[1]); w.w = pk2(hi[2], hi[3]); return __builtin_bit_cast(bf16x8, w); }
; __device__ __forceinline__ void s5_load_consts(S5C& K, const Args& a, int g, int lane) {
;     ...
;     const float* cre = a.in[I_CRE] + ((size_t)g * 16 + fr) * 64; const float* cim = a.in[I_CIM] + ((size_t)g * 16 + fr) * 64;
; #pragma unroll
;     for (int j = 0; j < 4; ++j) { const f32x4 r4 = *(const f32x4*)(cre + 16 * j + 4 * q), i4 = *(const f32x4*)(cim + 16 * j + 4 * q); K.Cf[j] = pack8(r4, -i4); }
; __device__ __forceinline__ void s5_prompt_task(const Args& a, const Ctx& C, int b, int g, v4u (&xv)[8]) {
;     ...
;     for (int t = 0; t < 4; ++t) zq[t] = __builtin_nontemporal_load((const v2u*)(ZBg + (size_t)(16 * chunk + t) * 16 + 4 * q));
;     LDS_WAIT();
;     { const float* A16 = (const float*)(a.ws + WS_S5C + S5C_A16) + (size_t)g * 128; const float* A256 = (const float*)(a.ws + WS_S5C + S5C_A256) + (size_t)g * 128;
;       const float a16r = A16[2 * lane], a16i = A16[2 * lane + 1], a256r = A256[2 * lane], a256i = A256[2 * lane + 1];
;       v2f sv[16];
; #pragma unroll
;       for (int i = 0; i < 16; ++i) sv[i] = *(const LAS v2f*)(SH + (16 * w + i) * 132 + 2 * lane);
;       float tr = 0.f, ti = 0.f;
; #pragma unroll
;       for (int i = 0; i < 16; ++i) { const float nr = a16r * tr - a16i * ti + sv[i][0], ni = a16r * ti + a16i * tr + sv[i][1]; tr = nr; ti = ni; }
;       TW[w * 128 + 2 * lane] = tr; TW[w * 128 + 2 * lane + 1] = ti;
	v_or_b32_e32 v82, 2, v7
	v_mov_b32_e32 v83, v111
	v_or_b32_e32 v84, 3, v7
	v_mov_b32_e32 v85, v111
	ds_write_b128 v3, v[100:103]
	ds_write_b128 v3, v[104:107] offset:400
	v_lshl_add_u64 v[78:79], v[138:139], 0, v[78:79]
	v_lshlrev_b64 v[80:81], 5, v[80:81]
	v_lshlrev_b64 v[82:83], 5, v[82:83]
	v_lshlrev_b64 v[84:85], 5, v[84:85]
	v_lshl_add_u64 v[80:81], v[138:139], 0, v[80:81]
	v_lshl_add_u64 v[82:83], v[138:139], 0, v[82:83]
	v_lshl_add_u64 v[84:85], v[138:139], 0, v[84:85]
	v_lshrrev_b32_e32 v244, 4, v162
	v_lshlrev_b32_e32 v244, 3, v244
	v_mov_b32_e32 v245, 0
	v_lshl_add_u64 v[78:79], v[78:79], 0, v[244:245]
	v_lshl_add_u64 v[82:83], v[82:83], 0, v[244:245]
	global_load_dwordx4 v[226:229], v[78:79], off nt
	global_load_dwordx4 v[230:233], v[82:83], off nt
	v_readlane_b32 s40, v249, 0
	s_and_b32 s40, s40, 63
	s_lshl_b32 s40, s40, 12
	v_and_b32_e32 v239, 15, v162
	v_lshrrev_b32_e32 v240, 4, v162
	v_lshlrev_b32_e32 v239, 8, v239
	v_lshl_add_u32 v239, v240, 4, v239
	v_add_u32_e32 v239, s40, v239
	global_load_dwordx4 v[58:61], v239, s[14:15]
	global_load_dwordx4 v[50:53], v239, s[14:15] offset:64
	global_load_dwordx4 v[62:65], v239, s[16:17]
	global_load_dwordx4 v[54:57], v239, s[16:17] offset:64
	global_load_dwordx4 v[42:45], v239, s[14:15] offset:128
	global_load_dwordx4 v[34:37], v239, s[14:15] offset:192
	global_load_dwordx4 v[46:49], v239, s[16:17] offset:128
	global_load_dwordx4 v[38:41], v239, s[16:17] offset:192
	v_lshl_add_u64 v[78:79], s[6:7], 0, v[152:153]
	v_add_co_u32_e32 v80, vcc, s2, v78
	s_waitcnt lgkmcnt(0)
	s_mov_b32 s2, 0x2310000
	s_nop 0
	v_addc_co_u32_e32 v81, vcc, 0, v79, vcc
	v_add_co_u32_e32 v78, vcc, s2, v78
	v_add_u32_e32 v7, s8, v152
	s_nop 0
	v_addc_co_u32_e32 v79, vcc, 0, v79, vcc
	s_mul_i32 s4, s82, 0x2100
	v_add_u32_e32 v7, s4, v7
	v_add_u32_e32 v11, 0x800, v7
	ds_read2_b64 v[106:109], v7 offset1:66
	ds_read2_b64 v[102:105], v7 offset0:132 offset1:198
	ds_read2_b64 v[98:101], v11 offset0:8 offset1:74
	ds_read2_b64 v[94:97], v11 offset0:140 offset1:206
	v_add_u32_e32 v11, 0x1000, v7
	ds_read2_b64 v[90:93], v11 offset0:16 offset1:82
	ds_read2_b64 v[86:89], v11 offset0:148 offset1:214
	v_add_u32_e32 v11, 0x1800, v7
	ds_read2_b64 v[82:85], v11 offset0:24 offset1:90
	ds_read2_b64 v[78:81], v11 offset0:156 offset1:222
	s_lshl_b32 s4, s82, 9
	s_add_i32 s4, s4, 0
	s_mov_b32 s2, 0
	s_cmp_lt_u32 s84, 64
	s_waitcnt vmcnt(10)
	v_mov_b32_e32 v148, v234
	v_mov_b32_e32 v149, v235
	v_mov_b32_e32 v150, v236
	v_mov_b32_e32 v151, v237
	v_mul_f32_e32 v11, 0, v148
	v_mul_f32_e32 v155, 0, v149
	v_sub_f32_e32 v154, v11, v155
	v_fmac_f32_e32 v155, 0, v148
	s_waitcnt lgkmcnt(7)
	v_pk_add_f32 v[154:155], v[154:155], v[106:107]
	v_add_u32_e32 v11, s4, v152
	v_pk_mul_f32 v[156:157], v[148:149], v[154:155] op_sel:[1,1] op_sel_hi:[0,1]
	v_pk_fma_f32 v[158:159], v[148:149], v[154:155], v[156:157] op_sel_hi:[1,0,1]
	v_pk_fma_f32 v[156:157], v[148:149], v[154:155], v[156:157] op_sel_hi:[1,0,1] neg_lo:[0,0,1] neg_hi:[0,0,1]
	v_add_u32_e32 v11, 0x21000, v11
	v_mov_b32_e32 v157, v159
	v_pk_add_f32 v[156:157], v[108:109], v[156:157]
	v_mov_b32_e32 v152, v111
	v_pk_mul_f32 v[158:159], v[148:149], v[156:157] op_sel:[1,1] op_sel_hi:[0,1]
	v_pk_fma_f32 v[164:165], v[148:149], v[156:157], v[158:159] op_sel_hi:[1,0,1]
	v_pk_fma_f32 v[158:159], v[148:149], v[156:157], v[158:159] op_sel_hi:[1,0,1] neg_lo:[0,0,1] neg_hi:[0,0,1]
	s_nop 0
	v_mov_b32_e32 v159, v165
	s_waitcnt lgkmcnt(6)
	v_pk_add_f32 v[158:159], v[102:103], v[158:159]
	s_nop 0
	v_pk_mul_f32 v[164:165], v[148:149], v[158:159] op_sel:[1,1] op_sel_hi:[0,1]
	v_pk_fma_f32 v[166:167], v[148:149], v[158:159], v[164:165] op_sel_hi:[1,0,1]
	v_pk_fma_f32 v[164:165], v[148:149], v[158:159], v[164:165] op_sel_hi:[1,0,1] neg_lo:[0,0,1] neg_hi:[0,0,1]
	s_nop 0
	v_mov_b32_e32 v165, v167
	v_pk_add_f32 v[164:165], v[104:105], v[164:165]
	s_nop 0
	v_pk_mul_f32 v[166:167], v[148:149], v[164:165] op_sel:[1,1] op_sel_hi:[0,1]
	v_pk_fma_f32 v[168:169], v[148:149], v[164:165], v[166:167] op_sel_hi:[1,0,1]
	v_pk_fma_f32 v[166:167], v[148:149], v[164:165], v[166:167] op_sel_hi:[1,0,1] neg_lo:[0,0,1] neg_hi:[0,0,1]
	s_nop 0
	v_mov_b32_e32 v167, v169
	s_waitcnt lgkmcnt(5)
; __device__ __forceinline__ void s5_prompt_task(const Args& a, const Ctx& C, int b, int g, v4u (&xv)[8]) {
;     ...
;       float tr = 0.f, ti = 0.f;
; #pragma unroll
;       for (int i = 0; i < 16; ++i) { const float nr = a16r * tr - a16i * ti + sv[i][0], ni = a16r * ti + a16i * tr + sv[i][1]; tr = nr; ti = ni; }
;       TW[w * 128 + 2 * lane] = tr; TW[w * 128 + 2 * lane + 1] = ti;
;       __syncthreads();
;       float hr = 0.f, hi = 0.f;
;       for (int v = 0; v < w; ++v) { const float sr = TW[v * 128 + 2 * lane], si = TW[v * 128 + 2 * lane + 1];
;           const float nr = a256r * hr - a256i * hi + sr, ni = a256r * hi + a256i * hr + si; hr = nr; hi = ni; }
	v_pk_add_f32 v[166:167], v[98:99], v[166:167]
	s_nop 0
	v_pk_mul_f32 v[168:169], v[148:149], v[166:167] op_sel:[1,1] op_sel_hi:[0,1]
	v_pk_fma_f32 v[170:171], v[148:149], v[166:167], v[168:169] op_sel_hi:[1,0,1]
	v_pk_fma_f32 v[168:169], v[148:149], v[166:167], v[168:169] op_sel_hi:[1,0,1] neg_lo:[0,0,1] neg_hi:[0,0,1]
	s_nop 0
	v_mov_b32_e32 v169, v171
	v_pk_add_f32 v[168:169], v[100:101], v[168:169]
	s_nop 0
	v_pk_mul_f32 v[170:171], v[148:149], v[168:169] op_sel:[1,1] op_sel_hi:[0,1]
	v_pk_fma_f32 v[172:173], v[148:149], v[168:169], v[170:171] op_sel_hi:[1,0,1]
	v_pk_fma_f32 v[170:171], v[148:149], v[168:169], v[170:171] op_sel_hi:[1,0,1] neg_lo:[0,0,1] neg_hi:[0,0,1]
	s_nop 0
	v_mov_b32_e32 v171, v173
	s_waitcnt lgkmcnt(4)
	v_pk_add_f32 v[170:171], v[94:95], v[170:171]
	s_nop 0
	v_pk_mul_f32 v[172:173], v[148:149], v[170:171] op_sel:[1,1] op_sel_hi:[0,1]
	v_pk_fma_f32 v[174:175], v[148:149], v[170:171], v[172:173] op_sel_hi:[1,0,1]
	v_pk_fma_f32 v[172:173], v[148:149], v[170:171], v[172:173] op_sel_hi:[1,0,1] neg_lo:[0,0,1] neg_hi:[0,0,1]
	s_nop 0
	v_mov_b32_e32 v173, v175
	v_pk_add_f32 v[172:173], v[96:97], v[172:173]
	s_nop 0
	v_pk_mul_f32 v[174:175], v[148:149], v[172:173] op_sel:[1,1] op_sel_hi:[0,1]
	v_pk_fma_f32 v[176:177], v[148:149], v[172:173], v[174:175] op_sel_hi:[1,0,1]
	v_pk_fma_f32 v[174:175], v[148:149], v[172:173], v[174:175] op_sel_hi:[1,0,1] neg_lo:[0,0,1] neg_hi:[0,0,1]
	s_nop 0
	v_mov_b32_e32 v175, v177
	s_waitcnt lgkmcnt(3)
	v_pk_add_f32 v[174:175], v[90:91], v[174:175]
	s_nop 0
	v_pk_mul_f32 v[176:177], v[148:149], v[174:175] op_sel:[1,1] op_sel_hi:[0,1]
	v_pk_fma_f32 v[178:179], v[148:149], v[174:175], v[176:177] op_sel_hi:[1,0,1]
	v_pk_fma_f32 v[176:177], v[148:149], v[174:175], v[176:177] op_sel_hi:[1,0,1] neg_lo:[0,0,1] neg_hi:[0,0,1]
	s_nop 0
	v_mov_b32_e32 v177, v179
	v_pk_add_f32 v[176:177], v[92:93], v[176:177]
	s_nop 0
	v_pk_mul_f32 v[178:179], v[148:149], v[176:177] op_sel:[1,1] op_sel_hi:[0,1]
	v_pk_fma_f32 v[180:181], v[148:149], v[176:177], v[178:179] op_sel_hi:[1,0,1]
	v_pk_fma_f32 v[178:179], v[148:149], v[176:177], v[178:179] op_sel_hi:[1,0,1] neg_lo:[0,0,1] neg_hi:[0,0,1]
	s_nop 0
	v_mov_b32_e32 v179, v181
	s_waitcnt lgkmcnt(2)
	v_pk_add_f32 v[178:179], v[86:87], v[178:179]
	s_nop 0
	v_pk_mul_f32 v[180:181], v[148:149], v[178:179] op_sel:[1,1] op_sel_hi:[0,1]
	v_pk_fma_f32 v[182:183], v[148:149], v[178:179], v[180:181] op_sel_hi:[1,0,1]
	v_pk_fma_f32 v[180:181], v[148:149], v[178:179], v[180:181] op_sel_hi:[1,0,1] neg_lo:[0,0,1] neg_hi:[0,0,1]
	s_nop 0
	v_mov_b32_e32 v181, v183
	v_pk_add_f32 v[182:183], v[88:89], v[180:181]
	s_nop 0
	v_pk_mul_f32 v[180:181], v[148:149], v[182:183] op_sel:[1,1] op_sel_hi:[0,1]
	v_pk_fma_f32 v[184:185], v[148:149], v[182:183], v[180:181] op_sel_hi:[1,0,1]
	v_pk_fma_f32 v[180:181], v[148:149], v[182:183], v[180:181] op_sel_hi:[1,0,1] neg_lo:[0,0,1] neg_hi:[0,0,1]
	s_nop 0
	v_mov_b32_e32 v181, v185
	s_waitcnt lgkmcnt(1)
	v_pk_add_f32 v[184:185], v[82:83], v[180:181]
	s_nop 0
	v_pk_mul_f32 v[180:181], v[148:149], v[184:185] op_sel:[1,1] op_sel_hi:[0,1]
	v_pk_fma_f32 v[186:187], v[148:149], v[184:185], v[180:181] op_sel_hi:[1,0,1]
	v_pk_fma_f32 v[180:181], v[148:149], v[184:185], v[180:181] op_sel_hi:[1,0,1] neg_lo:[0,0,1] neg_hi:[0,0,1]
	s_nop 0
	v_mov_b32_e32 v181, v187
	v_pk_add_f32 v[186:187], v[84:85], v[180:181]
	s_nop 0
	v_pk_mul_f32 v[180:181], v[148:149], v[186:187] op_sel:[1,1] op_sel_hi:[0,1]
	v_pk_fma_f32 v[188:189], v[148:149], v[186:187], v[180:181] op_sel_hi:[1,0,1]
	v_pk_fma_f32 v[180:181], v[148:149], v[186:187], v[180:181] op_sel_hi:[1,0,1] neg_lo:[0,0,1] neg_hi:[0,0,1]
	s_nop 0
	v_mov_b32_e32 v181, v189
	s_waitcnt lgkmcnt(0)
	v_pk_add_f32 v[188:189], v[78:79], v[180:181]
	s_nop 0
	v_pk_mul_f32 v[180:181], v[148:149], v[188:189] op_sel:[1,1] op_sel_hi:[0,1]
	v_pk_fma_f32 v[198:199], v[148:149], v[188:189], v[180:181] op_sel_hi:[1,0,1]
	v_pk_fma_f32 v[180:181], v[148:149], v[188:189], v[180:181] op_sel_hi:[1,0,1] neg_lo:[0,0,1] neg_hi:[0,0,1]
	s_nop 0
	v_mov_b32_e32 v181, v199
	v_pk_add_f32 v[180:181], v[80:81], v[180:181]
	ds_write_b64 v11, v[180:181]
	s_waitcnt lgkmcnt(0)
	s_barrier
	s_cbranch_scc1 .LBB0_985
	s_add_i32 s4, s82, -1
	s_cmp_lt_u32 s4, 7
	v_mov_b32_e32 v160, v111
	v_mov_b32_e32 v152, v111
	s_cbranch_scc1 .LBB0_977
	v_lshl_add_u32 v11, v162, 3, 0
	s_and_b32 s2, s82, 0x3fffff8
	s_waitcnt vmcnt(10)
	v_pk_mov_b32 v[154:155], v[150:151], v[150:151] op_sel:[1,0]
	s_mov_b32 s4, 0
	v_add_u32_e32 v11, 0x21000, v11
	v_mov_b32_e32 v152, 0
	v_mov_b32_e32 v160, 0

; __device__ __forceinline__ void s5_prompt_task(const Args& a, const Ctx& C, int b, int g, v4u (&xv)[8]) {
;     ...
;       float hr = 0.f, hi = 0.f;
;       for (int v = 0; v < w; ++v) { const float sr = TW[v * 128 + 2 * lane], si = TW[v * 128 + 2 * lane + 1];
;           const float nr = a256r * hr - a256i * hi + sr, ni = a256r * hi + a256i * hr + si; hr = nr; hi = ni; }
.LBB0_977:
	s_bfe_u32 s4, s84, 0x30006
	v_pk_mov_b32 v[180:181], v[148:149], v[148:149] op_sel:[1,0]
	s_cmp_eq_u32 s4, 0
	s_cbranch_scc1 .LBB0_983
	s_lshl_b32 s2, s2, 9
	s_add_i32 s2, s2, 0
	v_lshl_add_u32 v11, v162, 3, s2
	s_waitcnt vmcnt(10)
	v_pk_mov_b32 v[154:155], v[150:151], v[150:151] op_sel:[1,0]
	v_add_u32_e32 v11, 0x21000, v11
	v_mov_b32_e32 v153, v160

; #define LAS __attribute__((address_space(3)))
; __device__ __forceinline__ void s5_prompt_task(const Args& a, const Ctx& C, int b, int g, v4u (&xv)[8]) {
;     ...
;       for (int v = 0; v < w; ++v) { const float sr = TW[v * 128 + 2 * lane], si = TW[v * 128 + 2 * lane + 1];
;           const float nr = a256r * hr - a256i * hi + sr, ni = a256r * hi + a256i * hr + si; hr = nr; hi = ni; }
; #pragma unroll
;       for (int i = 0; i < 16; ++i) { *(LAS v2f*)(SH + (16 * w + i) * 132 + 2 * lane) = (v2f){hr, hi};
;           const float nr = a16r * hr - a16i * hi + sv[i][0], ni = a16r * hi + a16i * hr + sv[i][1]; hr = nr; hi = ni; }
.LBB0_984:
	s_waitcnt vmcnt(10)
	v_pk_mul_f32 v[150:151], v[180:181], v[152:153] op_sel:[0,1]
	s_nop 0
	v_pk_fma_f32 v[154:155], v[148:149], v[152:153], v[150:151] op_sel_hi:[1,0,1]
	v_pk_fma_f32 v[150:151], v[148:149], v[152:153], v[150:151] op_sel_hi:[1,0,1] neg_lo:[0,0,1] neg_hi:[0,0,1]
	s_nop 0
	v_mov_b32_e32 v151, v155
	v_pk_add_f32 v[154:155], v[106:107], v[150:151]
	s_nop 0
	v_pk_mul_f32 v[106:107], v[180:181], v[154:155] op_sel:[0,1]
	s_nop 0
	v_pk_fma_f32 v[150:151], v[148:149], v[154:155], v[106:107] op_sel_hi:[1,0,1]
	v_pk_fma_f32 v[106:107], v[148:149], v[154:155], v[106:107] op_sel_hi:[1,0,1] neg_lo:[0,0,1] neg_hi:[0,0,1]
	s_nop 0
	v_mov_b32_e32 v107, v151
	v_pk_add_f32 v[156:157], v[108:109], v[106:107]
	s_nop 0
	v_pk_mul_f32 v[106:107], v[180:181], v[156:157] op_sel:[0,1]
	s_nop 0
	v_pk_fma_f32 v[108:109], v[148:149], v[156:157], v[106:107] op_sel_hi:[1,0,1]
	v_pk_fma_f32 v[106:107], v[148:149], v[156:157], v[106:107] op_sel_hi:[1,0,1] neg_lo:[0,0,1] neg_hi:[0,0,1]
	s_nop 0
	v_mov_b32_e32 v107, v109
	v_pk_add_f32 v[158:159], v[102:103], v[106:107]
	s_nop 0
	v_pk_mul_f32 v[102:103], v[180:181], v[158:159] op_sel:[0,1]
	s_nop 0
	v_pk_fma_f32 v[106:107], v[148:149], v[158:159], v[102:103] op_sel_hi:[1,0,1]
	v_pk_fma_f32 v[102:103], v[148:149], v[158:159], v[102:103] op_sel_hi:[1,0,1] neg_lo:[0,0,1] neg_hi:[0,0,1]
	s_nop 0
	v_mov_b32_e32 v103, v107
	v_pk_add_f32 v[164:165], v[104:105], v[102:103]
	s_nop 0
	v_pk_mul_f32 v[102:103], v[180:181], v[164:165] op_sel:[0,1]
	s_nop 0
	v_pk_fma_f32 v[104:105], v[148:149], v[164:165], v[102:103] op_sel_hi:[1,0,1]
	v_pk_fma_f32 v[102:103], v[148:149], v[164:165], v[102:103] op_sel_hi:[1,0,1] neg_lo:[0,0,1] neg_hi:[0,0,1]
	s_nop 0
	v_mov_b32_e32 v103, v105
	v_pk_add_f32 v[166:167], v[98:99], v[102:103]
	s_nop 0
	v_pk_mul_f32 v[98:99], v[180:181], v[166:167] op_sel:[0,1]
	s_nop 0
	v_pk_fma_f32 v[102:103], v[148:149], v[166:167], v[98:99] op_sel_hi:[1,0,1]
	v_pk_fma_f32 v[98:99], v[148:149], v[166:167], v[98:99] op_sel_hi:[1,0,1] neg_lo:[0,0,1] neg_hi:[0,0,1]
	s_nop 0
	v_mov_b32_e32 v99, v103
	v_pk_add_f32 v[168:169], v[100:101], v[98:99]
	s_nop 0
	v_pk_mul_f32 v[98:99], v[180:181], v[168:169] op_sel:[0,1]
	s_nop 0
	v_pk_fma_f32 v[100:101], v[148:149], v[168:169], v[98:99] op_sel_hi:[1,0,1]
	v_pk_fma_f32 v[98:99], v[148:149], v[168:169], v[98:99] op_sel_hi:[1,0,1] neg_lo:[0,0,1] neg_hi:[0,0,1]
	s_nop 0
	v_mov_b32_e32 v99, v101
	v_pk_add_f32 v[170:171], v[94:95], v[98:99]
	s_nop 0
	v_pk_mul_f32 v[94:95], v[180:181], v[170:171] op_sel:[0,1]
	s_nop 0
	v_pk_fma_f32 v[98:99], v[148:149], v[170:171], v[94:95] op_sel_hi:[1,0,1]
	v_pk_fma_f32 v[94:95], v[148:149], v[170:171], v[94:95] op_sel_hi:[1,0,1] neg_lo:[0,0,1] neg_hi:[0,0,1]
	s_nop 0
	v_mov_b32_e32 v95, v99
	v_pk_add_f32 v[172:173], v[96:97], v[94:95]
	s_nop 0
	v_pk_mul_f32 v[94:95], v[180:181], v[172:173] op_sel:[0,1]
	s_nop 0
	v_pk_fma_f32 v[96:97], v[148:149], v[172:173], v[94:95] op_sel_hi:[1,0,1]
	v_pk_fma_f32 v[94:95], v[148:149], v[172:173], v[94:95] op_sel_hi:[1,0,1] neg_lo:[0,0,1] neg_hi:[0,0,1]
	s_nop 0
	v_mov_b32_e32 v95, v97
	v_pk_add_f32 v[174:175], v[90:91], v[94:95]
	s_nop 0
	v_pk_mul_f32 v[90:91], v[180:181], v[174:175] op_sel:[0,1]
	s_nop 0
	v_pk_fma_f32 v[94:95], v[148:149], v[174:175], v[90:91] op_sel_hi:[1,0,1]
	v_pk_fma_f32 v[90:91], v[148:149], v[174:175], v[90:91] op_sel_hi:[1,0,1] neg_lo:[0,0,1] neg_hi:[0,0,1]
	s_nop 0
	v_mov_b32_e32 v91, v95
	v_pk_add_f32 v[176:177], v[92:93], v[90:91]
	s_nop 0
	v_pk_mul_f32 v[90:91], v[180:181], v[176:177] op_sel:[0,1]
	s_nop 0
	v_pk_fma_f32 v[92:93], v[148:149], v[176:177], v[90:91] op_sel_hi:[1,0,1]
	v_pk_fma_f32 v[90:91], v[148:149], v[176:177], v[90:91] op_sel_hi:[1,0,1] neg_lo:[0,0,1] neg_hi:[0,0,1]
	s_nop 0
	v_mov_b32_e32 v91, v93
	v_pk_add_f32 v[178:179], v[86:87], v[90:91]
	s_nop 0
	v_pk_mul_f32 v[86:87], v[180:181], v[178:179] op_sel:[0,1]
	s_nop 0
	v_pk_fma_f32 v[90:91], v[148:149], v[178:179], v[86:87] op_sel_hi:[1,0,1]
	v_pk_fma_f32 v[86:87], v[148:149], v[178:179], v[86:87] op_sel_hi:[1,0,1] neg_lo:[0,0,1] neg_hi:[0,0,1]
	s_nop 0
	v_mov_b32_e32 v87, v91
	v_pk_add_f32 v[182:183], v[88:89], v[86:87]
	s_nop 0
	v_pk_mul_f32 v[86:87], v[180:181], v[182:183] op_sel:[0,1]
	s_nop 0
	v_pk_fma_f32 v[88:89], v[148:149], v[182:183], v[86:87] op_sel_hi:[1,0,1]
	v_pk_fma_f32 v[86:87], v[148:149], v[182:183], v[86:87] op_sel_hi:[1,0,1] neg_lo:[0,0,1] neg_hi:[0,0,1]
	s_nop 0
	v_mov_b32_e32 v87, v89
	v_pk_add_f32 v[184:185], v[82:83], v[86:87]
	s_nop 0
	v_pk_mul_f32 v[82:83], v[180:181], v[184:185] op_sel:[0,1]
	s_nop 0
	v_pk_fma_f32 v[86:87], v[148:149], v[184:185], v[82:83] op_sel_hi:[1,0,1]
	v_pk_fma_f32 v[82:83], v[148:149], v[184:185], v[82:83] op_sel_hi:[1,0,1] neg_lo:[0,0,1] neg_hi:[0,0,1]
	s_nop 0
	v_mov_b32_e32 v83, v87
	v_pk_add_f32 v[186:187], v[84:85], v[82:83]
	s_nop 0
	v_pk_mul_f32 v[82:83], v[180:181], v[186:187] op_sel:[0,1]
	s_nop 0
	v_pk_fma_f32 v[84:85], v[148:149], v[186:187], v[82:83] op_sel_hi:[1,0,1]
	v_pk_fma_f32 v[82:83], v[148:149], v[186:187], v[82:83] op_sel_hi:[1,0,1] neg_lo:[0,0,1] neg_hi:[0,0,1]
	s_nop 0
	v_mov_b32_e32 v83, v85
	v_pk_add_f32 v[188:189], v[78:79], v[82:83]
	s_nop 0
	v_pk_mul_f32 v[78:79], v[180:181], v[188:189] op_sel:[0,1]
	s_nop 0
	v_pk_fma_f32 v[82:83], v[148:149], v[188:189], v[78:79] op_sel_hi:[1,0,1]
	v_pk_fma_f32 v[78:79], v[148:149], v[188:189], v[78:79] op_sel_hi:[1,0,1] neg_lo:[0,0,1] neg_hi:[0,0,1]
	s_nop 0
	v_mov_b32_e32 v79, v83
	v_pk_add_f32 v[180:181], v[80:81], v[78:79]

; #define LAS __attribute__((address_space(3)))
; __device__ __forceinline__ unsigned pk2(float lo, float hi) { return pg8::cvt_pk_bf16(lo, hi); }
; __device__ __forceinline__ bf16x8 pack8(f32x4 lo, f32x4 hi) { v4u w; w.x = pk2(lo[0], lo[1]); w.y = pk2(lo[2], lo[3]); w.z = pk2(hi[0], hi[1]); w.w = pk2(hi[2], hi[3]); return __builtin_bit_cast(bf16x8, w); }
; __device__ __forceinline__ void s5_load_consts(S5C& K, const Args& a, int g, int lane) {
;     ...
;     const float* cre = a.in[I_CRE] + ((size_t)g * 16 + fr) * 64; const float* cim = a.in[I_CIM] + ((size_t)g * 16 + fr) * 64;
; #pragma unroll
;     for (int j = 0; j < 4; ++j) { const f32x4 r4 = *(const f32x4*)(cre + 16 * j + 4 * q), i4 = *(const f32x4*)(cim + 16 * j + 4 * q); K.Cf[j] = pack8(r4, -i4); }
;     const float* wg = a.in[I_WGLU] + (size_t)g * 512;
;     { f32x4 v, gt;
; #pragma unroll
;       for (int e = 0; e < 4; ++e) { v[e] = wg[(4 * q + e) * 32 + fr]; gt[e] = wg[(4 * q + e) * 32 + 16 + fr]; }
;       K.Wv = (v2u){pk2(v[0], v[1]), pk2(v[2], v[3])}; K.Wg = (v2u){pk2(gt[0], gt[1]), pk2(gt[2], gt[3])}; }
; __device__ __forceinline__ void s5_prompt_task(const Args& a, const Ctx& C, int b, int g, v4u (&xv)[8]) {
;     ...
;     for (int j = 0; j < 4; ++j) { const LAS float* s = SH + chunk * 132 + 2 * (16 * j + 4 * q); const f32x4 x0 = *(const LAS f32x4*)s, x1 = *(const LAS f32x4*)(s + 4);
;         hre[j] = (f32x4){x0[0], x0[2], x1[0], x1[2]}; him[j] = (f32x4){x0[1], x0[3], x1[1], x1[3]}; }
; #pragma unroll 1
.LBB0_987:
	s_waitcnt vmcnt(0)
	v_xor_b32_e32 v15, 0x80000000, v63
	v_xor_b32_e32 v32, 0x80000000, v62
	v_xor_b32_e32 v7, 0x80000000, v65
	v_xor_b32_e32 v11, 0x80000000, v64
	v_cvt_pk_bf16_f32 v32, v32, v15
	v_xor_b32_e32 v15, 0x80000000, v55
	v_xor_b32_e32 v54, 0x80000000, v54
	v_cvt_pk_bf16_f32 v33, v11, v7
	v_xor_b32_e32 v7, 0x80000000, v57
	v_xor_b32_e32 v11, 0x80000000, v56
	v_cvt_pk_bf16_f32 v50, v50, v51
	v_cvt_pk_bf16_f32 v51, v52, v53
	v_cvt_pk_bf16_f32 v52, v54, v15
	v_xor_b32_e32 v15, 0x80000000, v47
	v_xor_b32_e32 v46, 0x80000000, v46
	v_cvt_pk_bf16_f32 v53, v11, v7
	v_xor_b32_e32 v7, 0x80000000, v49
	v_xor_b32_e32 v11, 0x80000000, v48
	v_cvt_pk_bf16_f32 v42, v42, v43
	v_cvt_pk_bf16_f32 v43, v44, v45
	v_cvt_pk_bf16_f32 v44, v46, v15
	v_xor_b32_e32 v15, 0x80000000, v39
	v_xor_b32_e32 v38, 0x80000000, v38
	s_waitcnt lgkmcnt(0)
	v_cvt_pk_bf16_f32 v30, v58, v59
	v_cvt_pk_bf16_f32 v31, v60, v61
	v_cvt_pk_bf16_f32 v45, v11, v7
	v_xor_b32_e32 v7, 0x80000000, v41
	v_xor_b32_e32 v11, 0x80000000, v40
	v_cvt_pk_bf16_f32 v34, v34, v35
	v_cvt_pk_bf16_f32 v35, v36, v37
	v_cvt_pk_bf16_f32 v36, v38, v15
	ds_read_b128 v[46:49], v3
	ds_read_b128 v[78:81], v3 offset:16
	ds_read_b128 v[54:57], v3 offset:128
	ds_read_b128 v[82:85], v3 offset:144
	ds_read_b128 v[38:41], v3 offset:256
	s_waitcnt vmcnt(10)
	ds_read_b128 v[148:151], v3 offset:272
	ds_read_b128 v[58:61], v3 offset:384
	ds_read_b128 v[152:155], v3 offset:400
	s_lshl_b64 s[4:5], s[70:71], 22
	v_lshlrev_b64 v[62:63], 11, v[110:111]
	v_lshl_add_u64 v[62:63], s[4:5], 0, v[62:63]
	v_or_b32_e32 v62, s1, v62
	v_lshl_add_u64 v[62:63], v[62:63], 0, v[112:113]
	v_lshl_add_u64 v[62:63], s[94:95], 0, v[62:63]
	s_mov_b64 s[0:1], 0x9801c00
	v_cvt_pk_bf16_f32 v37, v11, v7
	v_cvt_pk_bf16_f32 v102, v191, v193
	v_cvt_pk_bf16_f32 v103, v195, v196
	v_cvt_pk_bf16_f32 v104, v161, v190
	v_cvt_pk_bf16_f32 v105, v192, v194
	v_lshl_add_u64 v[106:107], v[62:63], 0, s[0:1]
	s_mov_b32 s0, 0
	s_mov_b32 s1, 0xc3e00000
	v_mov_b32_e32 v109, 0
	s_movk_i32 s2, 0xf000
	s_mov_b64 s[4:5], 0x2000
	v_mov_b32_e32 v111, 0x43e00000
	s_waitcnt lgkmcnt(7)
	v_mov_b32_e32 v62, v47
	v_mov_b32_e32 v63, v49
	s_waitcnt lgkmcnt(6)
	v_mov_b32_e32 v64, v79
	v_mov_b32_e32 v65, v81
	s_waitcnt lgkmcnt(5)
	v_mov_b32_e32 v66, v55
	v_mov_b32_e32 v67, v57
	s_waitcnt lgkmcnt(4)
	v_mov_b32_e32 v68, v83
	v_mov_b32_e32 v69, v85
	s_waitcnt lgkmcnt(3)
	v_mov_b32_e32 v70, v39
	v_mov_b32_e32 v71, v41
	s_waitcnt lgkmcnt(2)
	v_mov_b32_e32 v72, v149
	v_mov_b32_e32 v73, v151
	s_waitcnt lgkmcnt(1)
	v_mov_b32_e32 v74, v59
	v_mov_b32_e32 v75, v61
	s_waitcnt lgkmcnt(0)
	v_mov_b32_e32 v76, v153
	v_mov_b32_e32 v77, v155
	v_mov_b32_e32 v47, v48
	v_mov_b32_e32 v48, v78
	v_mov_b32_e32 v49, v80
	v_mov_b32_e32 v55, v56
	v_mov_b32_e32 v56, v82
	v_mov_b32_e32 v57, v84
	v_mov_b32_e32 v39, v40
	v_mov_b32_e32 v40, v148
	v_mov_b32_e32 v41, v150
	v_mov_b32_e32 v59, v60
	v_mov_b32_e32 v60, v152
	v_mov_b32_e32 v61, v154
